# group barrier: L1 invalidate issued by wave 1 ahead of the opening barrier, single-XCC groups poll the arrival counter directly; la_unit loads pipelined; P0 item loads in flight together
# speedup vs baseline: 1.0043x; 1.0043x over previous
; __device__ __forceinline__ void grp_barrier(const XcdBarrier& b, unsigned gsz) {
;     ...
;     __syncthreads();
; __global__ void __launch_bounds__(NTHREADS, 2) hybrid_fwd(Args Aval) {
;     ...
; #pragma unroll 1
;     for (int l = 0; l < 4; ++l) {
.LBB0_170:
	s_or_b64 exec, exec, s[0:1]
	s_add_u32 s46, s46, 1
	s_addc_u32 s47, s47, 0
	s_cmp_eq_u32 s46, 4
	s_waitcnt vmcnt(0)
	s_barrier
	s_cbranch_scc0 .LBB0_171
	s_getpc_b64 s[98:99]

; __device__ __forceinline__ void grp_barrier(const XcdBarrier& b, unsigned gsz) {
;     asm volatile("s_waitcnt vmcnt(0)" ::: "memory");
;     __syncthreads();
.LBB0_248:
	s_mov_b64 s[4:5], s[48:49]
	s_mov_b32 s6, s2
	s_getreg_b32 s3, hwreg(HW_REG_XCC_ID, 0, 4)
	s_waitcnt vmcnt(0)
	s_waitcnt vmcnt(0)
	v_readfirstlane_b32 s0, v0
	s_nop 3
	s_lshr_b32 s0, s0, 6
	s_cmp_eq_u32 s0, 1
	s_cbranch_scc0 .Lgb_noinv0
	buffer_inv sc1

; __device__ __forceinline__ unsigned xb_ld(unsigned* p)              { return __hip_atomic_load(p, __ATOMIC_RELAXED, __HIP_MEMORY_SCOPE_AGENT); }
; __device__ __forceinline__ unsigned xb_add(unsigned* p, unsigned v) { return __hip_atomic_fetch_add(p, v, __ATOMIC_RELAXED, __HIP_MEMORY_SCOPE_AGENT); }
; #define XB_SPIN(cond, bar) do { unsigned _sp = 0; while (cond) { __builtin_amdgcn_s_sleep(1); \
;     if ((++_sp & 255u) == 0u) { if (xb_ld(&(bar)[XB_TMO])) break; if (_sp > XB_SPIN_CAP) { atomicAdd(&(bar)[XB_TMO], 1u); break; } } } } while (0)
; __device__ __forceinline__ void grp_barrier(const XcdBarrier& b, unsigned gsz) {
;     ...
;         const unsigned old = xb_add(&bar[XB_XSUB(b.x)], 1u);
;         const bool early = (nx == 1u);
;         if (early) __builtin_amdgcn_fence(__ATOMIC_ACQUIRE, "agent");
;         const unsigned gen = old / nloc;
;         if (old + 1u == (gen + 1u) * nloc) {
;             if (nx > 1u) __builtin_amdgcn_fence(__ATOMIC_RELEASE, "agent");
;             if (!early) asm volatile("s_waitcnt vmcnt(0)" ::: "memory");
;             if (!early) {
;             const unsigned og = xb_add(&bar[XB_TOP], 1u);
;             const unsigned tg = og / nx;
;             if (og + 1u == (tg + 1u) * nx) xb_add(&bar[XB_TOPGEN], 1u);
;             else XB_SPIN(xb_ld(&bar[XB_TOPGEN]) == tg, bar);
;             }
;             if (!early) __builtin_amdgcn_fence(__ATOMIC_ACQUIRE, "agent");
;             xb_add(&bar[XB_XGEN(b.x)], 1u);
;             asm volatile("s_waitcnt vmcnt(0)" ::: "memory");
;         } else {
;             XB_SPIN(xb_ld(&bar[XB_XGEN(b.x)]) == gen, bar);
.LBB0_266:
	s_or_b64 exec, exec, s[10:11]
	s_waitcnt lgkmcnt(0)
	v_cmp_eq_u32_e32 vcc, 1, v4
	s_cbranch_vccz .Lgb_slow0
	global_load_dword v7, v202, s[8:9] offset:1024 sc1
	s_mov_b32 s3, 0
	s_waitcnt vmcnt(1)
	v_and_b32_e32 v3, 31, v6
	v_and_b32_e32 v6, 0xffffffe0, v6
	v_cmp_eq_u32_e32 vcc, 31, v3
	v_add_u32_e32 v6, 32, v6
	s_cbranch_vccz .Lgb_poll0
	global_atomic_add v203, v205, s[8:9] offset:1024
	s_branch .Lgb_done0
.Lgb_poll0:
	s_waitcnt vmcnt(0)
	v_sub_u32_e32 v3, v7, v6
	v_cmp_gt_i32_e32 vcc, 0, v3
	s_cbranch_vccz .Lgb_done0
	s_sleep 1
	s_add_u32 s3, s3, 1
	s_cmp_lt_u32 s3, 0x40000
	s_cbranch_scc0 .Lgb_done0
	global_load_dword v7, v202, s[8:9] offset:1024 sc1
	s_branch .Lgb_poll0

; __device__ __forceinline__ void grp_barrier(const XcdBarrier& b, unsigned gsz) {
;     ...
;         const bool early = (nx == 1u);
;         if (early) __builtin_amdgcn_fence(__ATOMIC_ACQUIRE, "agent");
;         const unsigned gen = old / nloc;
;         if (old + 1u == (gen + 1u) * nloc) {
.Lgb_slow0:
	v_cmp_ne_u32_e64 s[4:5], 1, v4
	s_waitcnt vmcnt(0)
	v_readfirstlane_b32 s3, v6
	s_and_b64 vcc, exec, s[4:5]
	s_cbranch_vccnz .LBB0_268

; __device__ __forceinline__ void grp_barrier(const XcdBarrier& b, unsigned gsz) {
;     ...
;     __syncthreads();
; __global__ void __launch_bounds__(NTHREADS, 2) hybrid_fwd(Args Aval) {
;     ...
;             {   PHASE_BEGIN
;                 if (grp & 1) { for (int su = 64 * grp + rank; su < 64 * grp + 64; su += 32) { UNIT_BEGIN gla_sample_unit(A, lds, j, su, tid_u, wave_u, lane_u); } }
.LBB0_308:
	s_or_b64 exec, exec, s[0:1]
	s_mov_b64 s[6:7], s[48:49]
	s_mov_b32 s38, s2
	v_mov_b32_e32 v3, v0
	s_waitcnt vmcnt(0)
	s_barrier
	s_and_b32 s36, s38, 7
	s_ashr_i32 s37, s38, 3
	s_bitcmp0_b32 s38, 0
	s_cselect_b64 s[0:1], -1, 0
	s_cmp_gt_i32 s37, 63
	s_cselect_b64 s[4:5], -1, 0
	s_or_b64 s[4:5], s[4:5], s[0:1]
	s_and_b64 vcc, exec, s[4:5]
	s_cbranch_vccnz .LBB0_323
	s_lshl_b32 s3, s36, 6
	s_add_i32 s40, s3, s37
	s_bfe_u32 s39, s38, 0x20003
	s_or_b32 s43, s3, 32
	s_lshl_b32 s3, s36, 7
	s_lshl_b32 s4, s37, 1
	s_lshl_b32 s27, s94, 9
	s_lshl_b32 s41, s39, 7
	s_lshl_b32 s42, s39, 8
	s_add_i32 s54, s3, s4
	s_branch .LBB0_311

; __device__ __forceinline__ void grp_barrier(const XcdBarrier& b, unsigned gsz) {
;     asm volatile("s_waitcnt vmcnt(0)" ::: "memory");
;     __syncthreads();
.LBB0_356:
	s_mov_b64 s[4:5], s[48:49]
	s_mov_b32 s6, s2
	s_getreg_b32 s3, hwreg(HW_REG_XCC_ID, 0, 4)
	s_waitcnt vmcnt(0)
	s_waitcnt vmcnt(63) expcnt(7) lgkmcnt(15)
	v_readfirstlane_b32 s0, v0
	s_nop 3
	s_lshr_b32 s0, s0, 6
	s_cmp_eq_u32 s0, 1
	s_cbranch_scc0 .Lgb_noinv1
	buffer_inv sc1

; DI void gla_g3(ArgsP A, int j, int ebeg, int estep, int eend) {
;     const bf16* DS = (const bf16*)(A->ws + WS_DS); bf16* SC = (bf16*)(A->ws + WS_SC); const float* GD = (const float*)(A->ws + WS_GD);
;     for (int e = ebeg; e < eend; e += estep) {
;         const int vq = e & 63, k = (e >> 6) & 127, bh = e >> 13;
;         const size_t base = (size_t)bh * 32 * 32768 + (size_t)k * 256 + 4 * vq;
; __global__ void __launch_bounds__(NTHREADS, 2) hybrid_fwd(Args Aval) {
;     ...
;             {   PHASE_BEGIN
;                 gla_g3(A, j, 32768 * grp + rank * NTHREADS + tid, 32 * NTHREADS, 32768 * grp + 32768);
.LBB0_416:
	s_or_b64 exec, exec, s[0:1]
	s_mov_b64 s[8:9], s[48:49]
	s_mov_b32 s0, s2
	v_mov_b32_e32 v3, v0
	s_waitcnt vmcnt(0)
	s_barrier
	s_lshl_b32 s1, s0, 15
	s_lshl_b32 s0, s0, 6
	s_and_b32 s3, s1, 0x38000
	s_and_b32 s0, s0, 0xfffffe00
	s_add_i32 s0, s3, s0
	v_add_u32_e32 v3, s0, v3
	s_add_i32 s3, s3, 0x8000
	v_cmp_gt_i32_e32 vcc, s3, v3
	s_and_saveexec_b64 s[0:1], vcc
	s_cbranch_execz .LBB0_421
	s_load_dwordx4 s[4:7], s[8:9], 0x108
	s_lshl_b32 s8, s94, 5
	v_lshlrev_b32_e32 v30, 2, v3
	s_waitcnt lgkmcnt(0)
	v_lshl_add_u64 v[8:9], s[4:5], 0, v[168:169]
	s_mov_b64 s[4:5], 0

; __device__ __forceinline__ void grp_barrier(const XcdBarrier& b, unsigned gsz) {
;     asm volatile("s_waitcnt vmcnt(0)" ::: "memory");
;     __syncthreads();
.LBB0_421:
	s_or_b64 exec, exec, s[0:1]
	s_mov_b64 s[4:5], s[48:49]
	s_mov_b32 s6, s2
	s_getreg_b32 s3, hwreg(HW_REG_XCC_ID, 0, 4)
	s_waitcnt vmcnt(0)
	v_readfirstlane_b32 s0, v0
	s_nop 3
	s_lshr_b32 s0, s0, 6
	s_cmp_eq_u32 s0, 1
	s_cbranch_scc0 .Lgb_noinv2
	buffer_inv sc1

; #define LAS __attribute__((address_space(3)))
; DI void g4_prefetch(const float* LAg, const bf16* QKVG, const bf16* SCg, int u, int tid, G4Pre& P) {
;     const int h = u & 3, row0 = (u >> 2) * 64, di = ((u >> 7) * 4 + h) * 32 + ((u >> 2) & 31), k = tid & 127, tq = tid >> 7;
; #pragma unroll
;     for (int tt = 0; tt < 16; ++tt) P.la[tt] = LAg[(size_t)(row0 + 16 * tq + tt) * 512 + h * 128 + k];
; #pragma unroll
;     for (int i = 0; i < 2; ++i) { const int id = tid + 512 * i, t = id >> 4, c8 = id & 15; const bf16* rp = QKVG + (size_t)(row0 + t) * 3072 + h * 128 + c8 * 8; P.qv[i] = *(const u32x4*)rp; P.kv[i] = *(const u32x4*)(rp + 512); }
; #pragma unroll
;     for (int i = 0; i < 4; ++i) { const int id = tid + 512 * i, t = id >> 5, c8 = id & 31; P.vv[i] = *(const u32x4*)(QKVG + (size_t)(row0 + t) * 3072 + 1024 + h * 256 + c8 * 8); }
; #pragma unroll
;     for (int i = 0; i < 8; ++i) { const int id = tid + 512 * i; P.sc[i] = *(const u32x4*)(SCg + (size_t)di * 32768 + (size_t)id * 8); }
; }
; DI void gla_g4_prompt_all(ArgsP A, LAS unsigned char* lds, int j, int ubeg, int ustep, int uend, int tid0) {
;     LAS unsigned char* QIm = lds; LAS unsigned char* KIm = lds + 17408; LAS unsigned char* VI = lds + 34816; LAS unsigned char* SI = lds + 68608;
;     LAS float* RED = (LAS float*)(lds + 136192); LAS float* QT = (LAS float*)(lds + 137216);
;     const bf16* QKVG = (const bf16*)(A->ws + WS_QKVG); const float* LAg = (const float*)(A->ws + WS_LA); const bf16* SCg = (const bf16*)(A->ws + WS_SC);
;     bf16* OG = (bf16*)(A->ws + WS_A3);
;     G4Pre P;
;     if (ubeg < uend) g4_prefetch(LAg, QKVG, SCg, ubeg ^ 127, tid0, P);
.LBB0_481:
	s_or_b64 exec, exec, s[0:1]
	s_mov_b64 s[0:1], s[48:49]
	s_mov_b32 s3, s2
	v_mov_b32_e32 v170, v0
	s_waitcnt vmcnt(0)
	s_barrier
	s_load_dwordx2 s[4:5], s[0:1], 0x110
	s_lshl_b32 s0, s3, 7
	s_ashr_i32 s8, s3, 3
	s_and_b32 s3, s0, 0x380
	s_add_i32 s22, s3, s8
	s_waitcnt lgkmcnt(0)
	s_add_u32 s0, s4, 0x1f900000
	s_addc_u32 s1, s5, 0
	s_add_u32 s14, s4, 0x2e500000
	s_addc_u32 s15, s5, 0
	s_add_u32 s16, s4, 0x2a100000
	s_addc_u32 s17, s5, 0
	s_cmpk_lt_i32 s8, 0x80
	s_cselect_b64 s[6:7], -1, 0
	s_cmpk_gt_i32 s8, 0x7f
	s_cbranch_scc1 .LBB0_483
	s_xor_b32 s8, s22, 0x7f
	s_and_b32 s10, s8, 3
	s_ashr_i32 s8, s8, 2
	v_ashrrev_i32_e32 v4, 3, v170
	s_lshl_b32 s11, s8, 6
	v_and_b32_e32 v4, -16, v4
	s_and_b32 s12, s22, 0xffffff80
	s_and_b32 s13, s8, 31
	v_add_u32_e32 v4, s11, v4
	s_lshl_b32 s34, s10, 9
	v_and_b32_e32 v3, 0x7f, v170
	s_add_u32 s8, s14, s34
	v_or_b32_e32 v10, 1, v4
	v_or_b32_e32 v12, 2, v4
	v_or_b32_e32 v14, 3, v4
	v_or_b32_e32 v16, 4, v4
	v_or_b32_e32 v18, 5, v4
	v_or_b32_e32 v20, 6, v4
	s_addc_u32 s9, s15, 0
	v_lshlrev_b32_e32 v6, 2, v3
	v_mov_b32_e32 v7, v2
	v_ashrrev_i32_e32 v5, 31, v4
	v_ashrrev_i32_e32 v11, 31, v10
	v_ashrrev_i32_e32 v13, 31, v12
	v_ashrrev_i32_e32 v15, 31, v14
	v_ashrrev_i32_e32 v17, 31, v16
	v_ashrrev_i32_e32 v19, 31, v18
	v_ashrrev_i32_e32 v21, 31, v20
	v_or_b32_e32 v22, 7, v4
	v_lshl_add_u64 v[6:7], s[8:9], 0, v[6:7]
	v_lshlrev_b64 v[8:9], 11, v[4:5]
	v_lshlrev_b64 v[10:11], 11, v[10:11]
	v_lshlrev_b64 v[12:13], 11, v[12:13]
	v_lshlrev_b64 v[14:15], 11, v[14:15]
	v_lshlrev_b64 v[16:17], 11, v[16:17]
	v_lshlrev_b64 v[18:19], 11, v[18:19]
	v_lshlrev_b64 v[20:21], 11, v[20:21]
	v_ashrrev_i32_e32 v23, 31, v22
	v_lshl_add_u64 v[8:9], v[6:7], 0, v[8:9]
	v_lshl_add_u64 v[10:11], v[6:7], 0, v[10:11]
	v_lshl_add_u64 v[12:13], v[6:7], 0, v[12:13]
	v_lshl_add_u64 v[14:15], v[6:7], 0, v[14:15]
	v_lshl_add_u64 v[16:17], v[6:7], 0, v[16:17]
	v_lshl_add_u64 v[18:19], v[6:7], 0, v[18:19]
	v_lshl_add_u64 v[20:21], v[6:7], 0, v[20:21]
	v_lshlrev_b64 v[22:23], 11, v[22:23]
	v_lshl_add_u64 v[22:23], v[6:7], 0, v[22:23]
	global_load_dword v180, v[8:9], off
	global_load_dword v181, v[10:11], off
	global_load_dword v182, v[12:13], off
	global_load_dword v183, v[14:15], off
	global_load_dword v184, v[16:17], off
	global_load_dword v185, v[18:19], off
	global_load_dword v186, v[20:21], off
	global_load_dword v187, v[22:23], off
	v_or_b32_e32 v8, 8, v4
	v_or_b32_e32 v10, 9, v4
	v_or_b32_e32 v12, 10, v4
	v_or_b32_e32 v14, 11, v4
	v_or_b32_e32 v16, 12, v4
	v_or_b32_e32 v18, 13, v4
	v_or_b32_e32 v20, 14, v4
	v_or_b32_e32 v4, 15, v4
	v_ashrrev_i32_e32 v9, 31, v8
	v_ashrrev_i32_e32 v5, 31, v4
	s_lshl_b32 s8, s10, 5
	v_lshlrev_b64 v[8:9], 11, v[8:9]
	v_ashrrev_i32_e32 v11, 31, v10
	v_ashrrev_i32_e32 v13, 31, v12
	v_ashrrev_i32_e32 v15, 31, v14
	v_ashrrev_i32_e32 v17, 31, v16
	v_ashrrev_i32_e32 v19, 31, v18
	v_ashrrev_i32_e32 v21, 31, v20
	v_lshlrev_b64 v[4:5], 11, v[4:5]
	s_or_b32 s12, s8, s12
	s_lshl_b32 s8, s10, 8
	v_lshl_add_u64 v[8:9], v[6:7], 0, v[8:9]
	v_lshlrev_b64 v[10:11], 11, v[10:11]
	v_lshlrev_b64 v[12:13], 11, v[12:13]
	v_lshlrev_b64 v[14:15], 11, v[14:15]
	v_lshlrev_b64 v[16:17], 11, v[16:17]
	v_lshlrev_b64 v[18:19], 11, v[18:19]
	v_lshlrev_b64 v[20:21], 11, v[20:21]
	v_lshl_add_u64 v[4:5], v[6:7], 0, v[4:5]
	s_add_u32 s8, s0, s8
	v_lshlrev_b32_e32 v3, 4, v170
	v_lshl_add_u64 v[10:11], v[6:7], 0, v[10:11]
	v_lshl_add_u64 v[12:13], v[6:7], 0, v[12:13]
	v_lshl_add_u64 v[14:15], v[6:7], 0, v[14:15]
	v_lshl_add_u64 v[16:17], v[6:7], 0, v[16:17]
	v_lshl_add_u64 v[18:19], v[6:7], 0, v[18:19]
	v_lshl_add_u64 v[20:21], v[6:7], 0, v[20:21]
	global_load_dword v188, v[8:9], off
	global_load_dword v189, v[10:11], off
	global_load_dword v190, v[12:13], off
	global_load_dword v191, v[14:15], off
	global_load_dword v192, v[16:17], off
	global_load_dword v193, v[18:19], off
	global_load_dword v194, v[20:21], off
	global_load_dword v195, v[4:5], off
	s_addc_u32 s9, s1, 0
	v_and_b32_e32 v4, 0xf0, v3
	v_mov_b32_e32 v5, v2
	v_ashrrev_i32_e32 v6, 4, v170
	v_lshl_add_u64 v[4:5], s[8:9], 0, v[4:5]
	v_add_u32_e32 v6, s11, v6
	v_mad_i64_i32 v[6:7], s[8:9], v6, s91, v[4:5]
	global_load_dwordx4 v[84:87], v[6:7], off
	global_load_dwordx4 v[88:91], v[6:7], off offset:1024
	v_add_u32_e32 v6, 0x200, v170
	v_ashrrev_i32_e32 v7, 4, v6
	v_add_u32_e32 v7, s11, v7
	v_mad_i64_i32 v[4:5], s[8:9], v7, s91, v[4:5]
	global_load_dwordx4 v[92:95], v[4:5], off
	global_load_dwordx4 v[96:99], v[4:5], off offset:1024
	v_ashrrev_i32_e32 v4, 5, v170
	v_add_u32_e32 v7, s11, v4
	v_mov_b64_e32 v[4:5], s[0:1]
	v_and_b32_e32 v10, 0x1f0, v3
	v_ashrrev_i32_e32 v3, 5, v6
	v_mad_i64_i32 v[8:9], s[8:9], v7, s91, v[4:5]
	v_add_u32_e32 v3, s11, v3
	v_lshl_add_u64 v[8:9], v[8:9], 0, s[34:35]
	v_mov_b32_e32 v11, v2
	v_mad_i64_i32 v[12:13], s[8:9], v3, s91, v[4:5]
	v_lshl_add_u64 v[8:9], v[8:9], 0, v[10:11]
	v_lshl_add_u64 v[12:13], v[12:13], 0, s[34:35]
	v_lshl_add_u64 v[12:13], v[12:13], 0, v[10:11]
	global_load_dwordx4 v[100:103], v[8:9], off offset:2048
	global_load_dwordx4 v[104:107], v[12:13], off offset:2048
	v_add_u32_e32 v8, 0x400, v170
	v_ashrrev_i32_e32 v3, 5, v8
	v_add_u32_e32 v3, s11, v3
	v_add_u32_e32 v14, 0x600, v170
	v_mad_i64_i32 v[12:13], s[8:9], v3, s91, v[4:5]
	v_ashrrev_i32_e32 v3, 5, v14
	v_add_u32_e32 v3, s11, v3
	v_mad_i64_i32 v[4:5], s[8:9], v3, s91, v[4:5]
	s_or_b32 s8, s12, s13
	s_ashr_i32 s9, s8, 31
	s_lshl_b64 s[8:9], s[8:9], 16
	v_lshl_add_u64 v[12:13], v[12:13], 0, s[34:35]
	v_lshl_add_u64 v[4:5], v[4:5], 0, s[34:35]
	s_add_u32 s8, s16, s8
	v_lshl_add_u64 v[12:13], v[12:13], 0, v[10:11]
	v_lshl_add_u64 v[4:5], v[4:5], 0, v[10:11]
	s_addc_u32 s9, s17, s9
	v_ashrrev_i32_e32 v171, 31, v170
	v_ashrrev_i32_e32 v7, 31, v6
	global_load_dwordx4 v[108:111], v[12:13], off offset:2048
	global_load_dwordx4 v[112:115], v[4:5], off offset:2048
	v_lshl_add_u64 v[4:5], v[170:171], 4, s[8:9]
	v_lshl_add_u64 v[6:7], v[6:7], 4, s[8:9]
	v_ashrrev_i32_e32 v9, 31, v8
	v_ashrrev_i32_e32 v15, 31, v14
	global_load_dwordx4 v[116:119], v[4:5], off
	global_load_dwordx4 v[120:123], v[6:7], off
	v_lshl_add_u64 v[6:7], v[8:9], 4, s[8:9]
	v_lshl_add_u64 v[8:9], v[14:15], 4, s[8:9]
	s_mov_b32 s8, 0x8000
	global_load_dwordx4 v[124:127], v[6:7], off
	global_load_dwordx4 v[128:131], v[8:9], off
	v_add_co_u32_e32 v6, vcc, s8, v4
	s_nop 1
	v_addc_co_u32_e32 v7, vcc, 0, v5, vcc
	v_add_co_u32_e32 v8, vcc, 0xa000, v4
	s_nop 1
	v_addc_co_u32_e32 v9, vcc, 0, v5, vcc
	global_load_dwordx4 v[132:135], v[6:7], off
	global_load_dwordx4 v[136:139], v[8:9], off
	v_add_co_u32_e32 v6, vcc, 0xc000, v4
	s_nop 1
	v_addc_co_u32_e32 v7, vcc, 0, v5, vcc
	v_add_co_u32_e32 v4, vcc, 0xe000, v4
	s_nop 1
	v_addc_co_u32_e32 v5, vcc, 0, v5, vcc
	global_load_dwordx4 v[140:143], v[6:7], off
	global_load_dwordx4 v[144:147], v[4:5], off

; __device__ __forceinline__ void grp_barrier(const XcdBarrier& b, unsigned gsz) {
;     asm volatile("s_waitcnt vmcnt(0)" ::: "memory");
;     __syncthreads();
.LBB0_541:
	s_mov_b32 s6, s2
	s_mov_b64 s[4:5], s[48:49]
	s_getreg_b32 s3, hwreg(HW_REG_XCC_ID, 0, 4)
	s_waitcnt vmcnt(0)
	s_waitcnt vmcnt(63) expcnt(7) lgkmcnt(15)
	v_readfirstlane_b32 s0, v0
	s_nop 3
	s_lshr_b32 s0, s0, 6
	s_cmp_eq_u32 s0, 1
	s_cbranch_scc0 .Lgb_noinv3
	buffer_inv sc1

; __device__ __forceinline__ void grp_barrier(const XcdBarrier& b, unsigned gsz) {
;     ...
;     __syncthreads();
; __global__ void __launch_bounds__(NTHREADS, 2) hybrid_fwd(Args Aval) {
;     ...
;         {   PHASE_BEGIN
;             const pg8::bf16_t* W = (l & 1) ? (const pg8::bf16_t*)(ws + WS_GLAWOUT) + (size_t)j * DM * DM : (const pg8::bf16_t*)(ws + WS_RGWOUT) + (size_t)j * DM * DM;
;             pg8::Gemm g{(const pg8::bf16_t*)(ws + WS_A3), W, MP, DM, DM}; pg8::GroupOrder S{8, 4, grp, rank};
;             pg8::BigEpi<pg8::XupdR8> E{{(pg8::bf16_t*)(ws + WS_XB), (float*)(ws + WS_SSQ), 1.f}};
;             pg8::gemm_phase<pg8::BigEpi<pg8::XupdR8>, pg8::GroupOrder, true, true>(lds, g, S, E, tid);
.LBB0_601:
	s_or_b64 exec, exec, s[0:1]
	s_mov_b64 s[4:5], 0
	s_waitcnt vmcnt(0)
	s_barrier

; __device__ __forceinline__ void grp_barrier(const XcdBarrier& b, unsigned gsz) {
;     asm volatile("s_waitcnt vmcnt(0)" ::: "memory");
;     __syncthreads();
.LBB0_751:
	s_or_b64 exec, exec, s[4:5]
	v_lshlrev_b64 v[4:5], 11, v[24:25]
	v_lshl_add_u64 v[4:5], v[16:17], 0, v[4:5]
	v_lshl_add_u64 v[4:5], v[30:31], 1, v[4:5]
	s_mov_b32 s6, s2
	s_mov_b64 s[4:5], s[48:49]
	global_store_dwordx4 v[4:5], v[8:11], off
	s_getreg_b32 s3, hwreg(HW_REG_XCC_ID, 0, 4)
	s_waitcnt vmcnt(0)
	s_waitcnt vmcnt(0)
	v_readfirstlane_b32 s0, v0
	s_nop 3
	s_lshr_b32 s0, s0, 6
	s_cmp_eq_u32 s0, 1
	s_cbranch_scc0 .Lgb_noinv4
	buffer_inv sc1

; #define PG8_STAGE(bufoff, gbase, voff) do { _Pragma("unroll") for (int _i = 0; _i < 2; ++_i) \
;         __builtin_amdgcn_global_load_lds((const unsigned*)((const char*)(gbase) + (voff)[_i]), (PG8_LAS unsigned*)(lds + (bufoff) + ldsw + _i * 8192), 16, 0, 0); } while (0)
; #define PG8_WAIT_V(n) asm volatile("s_waitcnt vmcnt(" #n ")" ::: "memory")
; #define PG8_BAR __builtin_amdgcn_s_barrier()
; template <class Epi, class Sched, bool ALIGN_EPI = false, bool SP2 = false>
; __device__ __forceinline__ void gemm_phase(PG8_LAS unsigned char* lds, const Gemm g, const Sched& S, const Epi& E, const int tid) {
;     ...
;     const char* cA = (const char*)g.A + (size_t)cur.pm * tstep; const char* cB = (const char*)g.Bt + (size_t)cur.pn * tstep;
;     S.a_ready(cur);
;     if constexpr (SP2) {
;         PG8_STAGE(PG8_SB(0, 0), cB, voffB); PG8_STAGE(PG8_SB(0, 1), cB + hstepB, voffB); PG8_STAGE(PG8_SA(0, 0), cA, voffA); PG8_STAGE(PG8_SA(0, 1), cA + hstep, voffA);
;         if (wr == 1) PG8_BAR;
;         PG8_WAIT_V(2); PG8_BAR;
;         PG8_STAGE(PG8_SB(1, 0), cB + kstep, voffB); PG8_STAGE(PG8_SA(1, 0), cA + kstep, voffA); PG8_STAGE(PG8_SB(1, 1), cB + hstepB + kstep, voffB);
;         PG8_WAIT_V(6); PG8_BAR;
.LBB0_813:
	s_or_b64 exec, exec, s[0:1]
	s_cmp_eq_u32 s46, 0
	v_readlane_b32 s0, v250, 0
	s_cselect_b64 s[4:5], -1, 0
	v_readlane_b32 s1, v250, 1
	v_writelane_b32 v250, s4, 10
	s_and_b64 s[0:1], s[0:1], s[4:5]
	s_andn2_b64 vcc, exec, s[0:1]
	s_waitcnt vmcnt(0)
	s_barrier
	v_writelane_b32 v250, s5, 11
	s_cbranch_vccnz .LBB0_828
	s_mov_b64 s[8:9], s[48:49]
	s_mov_b32 s1, s2
	v_mov_b32_e32 v3, v0
	s_ashr_i32 s0, s1, 3
	s_cmp_gt_i32 s0, 31
	v_readfirstlane_b32 s12, v3
	s_cbranch_scc1 .LBB0_828
	v_lshlrev_b32_e32 v6, 4, v3
	v_add_u32_e32 v7, 0x2000, v6
	v_ashrrev_i32_e32 v10, 31, v7
	v_lshrrev_b32_e32 v10, 22, v10
	v_add_u32_e32 v10, v7, v10
	v_ashrrev_i32_e32 v12, 10, v10
	v_mul_i32_i24_e32 v10, 0x400, v12
	v_sub_u32_e32 v7, v7, v10
	v_lshrrev_b32_e32 v10, 4, v7
	v_bitop3_b32 v7, v10, v7, 32 bitop3:0x6c
	v_ashrrev_i32_e32 v10, 31, v7
	v_lshrrev_b32_e32 v10, 26, v10
	v_add_u32_e32 v10, v7, v10
	v_lshlrev_b32_e32 v11, 3, v12
	v_ashrrev_i32_e32 v13, 6, v10
	v_and_b32_e32 v11, -16, v11
	v_add_u32_e32 v11, v13, v11
	v_lshrrev_b32_e32 v14, 2, v11
	v_lshlrev_b32_e32 v16, 1, v11
	v_and_b32_e32 v10, 0xc0, v10
	v_and_b32_e32 v14, 4, v14
	v_and_b32_e32 v15, 3, v13
	v_and_b32_e32 v16, 0x1fffd8, v16
	v_sub_u32_e32 v7, v7, v10
	v_or3_b32 v15, v15, v14, v16
	v_lshlrev_b32_e32 v14, 5, v12
	v_ashrrev_i16_sdwa v7, v205, sext(v7) dst_sel:DWORD dst_unused:UNUSED_PAD src0_sel:DWORD src1_sel:BYTE_0
	v_and_b32_e32 v16, 32, v14
	v_bfe_i32 v14, v7, 0, 16
	v_add_lshl_u32 v7, v16, v14, 1
	v_lshl_add_u32 v134, v15, 11, v7
	v_lshl_add_u32 v136, v11, 11, v7
	v_bfe_i32 v7, v3, 27, 1
	v_lshrrev_b32_e32 v7, 22, v7
	v_add_u32_e32 v7, v6, v7
	v_and_b32_e32 v7, 0xfffffc00, v7
	v_sub_u32_e32 v6, v6, v7
	v_lshrrev_b32_e32 v7, 4, v6
	v_ashrrev_i32_e32 v10, 31, v3
	v_bitop3_b32 v6, v7, v6, 32 bitop3:0x6c
	v_lshrrev_b32_e32 v10, 26, v10
	v_ashrrev_i32_e32 v7, 31, v6
	v_add_u32_e32 v10, v3, v10
	v_lshrrev_b32_e32 v7, 26, v7
	v_ashrrev_i32_e32 v16, 6, v10
	s_load_dwordx4 s[4:7], s[8:9], 0x108
	v_add_u32_e32 v7, v6, v7
	v_lshlrev_b32_e32 v10, 3, v16
	v_ashrrev_i32_e32 v15, 6, v7
	v_and_b32_e32 v10, -16, v10
	v_add_u32_e32 v10, v15, v10
	v_lshrrev_b32_e32 v11, 2, v10
	v_lshlrev_b32_e32 v18, 1, v10
	v_and_b32_e32 v7, 0xc0, v7
	v_and_b32_e32 v11, 4, v11
	v_and_b32_e32 v17, 3, v15
	v_and_b32_e32 v18, 0x1fffd8, v18
	v_sub_u32_e32 v6, v6, v7
	s_waitcnt lgkmcnt(0)
	v_mov_b32_e32 v133, s7
	v_mov_b32_e32 v132, s6
	s_mov_b64 s[6:7], 0xe700000
	v_or3_b32 v11, v17, v11, v18
	v_lshlrev_b32_e32 v17, 5, v16
	v_ashrrev_i16_sdwa v6, v205, sext(v6) dst_sel:DWORD dst_unused:UNUSED_PAD src0_sel:DWORD src1_sel:BYTE_0
	s_and_b32 s3, s1, 7
	v_lshl_add_u64 v[8:9], v[132:133], 0, s[6:7]
	s_mov_b64 s[6:7], 0x1100000
	s_ashr_i32 s14, s12, 6
	v_and_b32_e32 v18, 32, v17
	v_bfe_i32 v17, v6, 0, 16
	s_ashr_i32 s1, s0, 31
	v_lshl_add_u64 v[4:5], v[132:133], 0, s[6:7]
	s_lshl_b32 s27, s14, 10
	v_add_lshl_u32 v6, v18, v17, 1
	s_lshl_b64 s[6:7], s[0:1], 19
	v_lshl_add_u32 v138, v11, 11, v6
	v_lshl_add_u32 v140, v10, 11, v6
	v_lshl_add_u64 v[10:11], v[4:5], 0, s[6:7]
	s_add_i32 s1, s27, 0
	v_mov_b32_e32 v139, v2
	v_readfirstlane_b32 s24, v4
	v_readfirstlane_b32 s25, v5
	s_add_i32 m0, s1, 0x10000
	v_lshl_add_u64 v[4:5], v[10:11], 0, v[138:139]
	v_mov_b32_e32 v135, v2
	s_mov_b64 s[8:9], 0x10000
	v_readfirstlane_b32 s6, v10
	v_readfirstlane_b32 s7, v11
	global_load_lds_dwordx4 v[4:5], off
	v_lshl_add_u64 v[6:7], v[10:11], 0, v[134:135]
	s_add_i32 m0, s1, 0x12000
	v_lshl_add_u64 v[10:11], v[10:11], 0, s[8:9]
	s_lshl_b32 s34, s3, 19
	global_load_lds_dwordx4 v[6:7], off
	s_add_i32 m0, s1, 0x14000
	v_lshl_add_u64 v[18:19], v[10:11], 0, v[138:139]
	global_load_lds_dwordx4 v[18:19], off
	v_lshl_add_u64 v[10:11], v[10:11], 0, v[134:135]
	s_add_i32 m0, s1, 0x16000
	v_lshl_add_u64 v[18:19], v[8:9], 0, s[34:35]
	v_mov_b32_e32 v141, v2
	v_readfirstlane_b32 s22, v8
	v_readfirstlane_b32 s23, v9
	global_load_lds_dwordx4 v[10:11], off
	v_lshl_add_u64 v[8:9], v[18:19], 0, v[140:141]
	s_mov_b32 m0, s1
	v_mov_b32_e32 v137, v2
	s_add_i32 s28, s1, 0x2000
	v_readfirstlane_b32 s8, v18
	v_readfirstlane_b32 s9, v19
	global_load_lds_dwordx4 v[8:9], off
	v_lshl_add_u64 v[10:11], v[18:19], 0, v[136:137]
	s_mov_b32 m0, s28
	v_lshl_add_u64 v[18:19], v[18:19], 0, s[50:51]
	s_add_i32 s29, s1, 0x4000
	global_load_lds_dwordx4 v[10:11], off
	v_lshl_add_u64 v[20:21], v[18:19], 0, v[140:141]
	s_mov_b32 m0, s29
	s_add_i32 s30, s1, 0x6000
	global_load_lds_dwordx4 v[20:21], off
	v_lshl_add_u64 v[18:19], v[18:19], 0, v[136:137]
	s_mov_b32 m0, s30
	s_ashr_i32 s13, s12, 8
	global_load_lds_dwordx4 v[18:19], off
	s_cmp_eq_u32 s13, 1
	s_cselect_b64 s[10:11], -1, 0
	s_cmp_lg_u32 s13, 1
	s_cbranch_scc1 .LBB0_817
	s_barrier

; __device__ __forceinline__ void grp_barrier(const XcdBarrier& b, unsigned gsz) {
;     asm volatile("s_waitcnt vmcnt(0)" ::: "memory");
;     __syncthreads();
.LBB0_892:
	s_mov_b64 s[4:5], s[48:49]
	s_mov_b32 s6, s2
	s_getreg_b32 s3, hwreg(HW_REG_XCC_ID, 0, 4)
	s_waitcnt vmcnt(0)
	v_readfirstlane_b32 s0, v0
	s_nop 3
	s_lshr_b32 s0, s0, 6
	s_cmp_eq_u32 s0, 1
	s_cbranch_scc0 .Lgb_noinv5
	buffer_inv sc1

; #define PG8_STAGE(bufoff, gbase, voff) do { _Pragma("unroll") for (int _i = 0; _i < 2; ++_i) \
;         __builtin_amdgcn_global_load_lds((const unsigned*)((const char*)(gbase) + (voff)[_i]), (PG8_LAS unsigned*)(lds + (bufoff) + ldsw + _i * 8192), 16, 0, 0); } while (0)
; #define PG8_WAIT_V(n) asm volatile("s_waitcnt vmcnt(" #n ")" ::: "memory")
; #define PG8_BAR __builtin_amdgcn_s_barrier()
; template <class Epi, class Sched, bool ALIGN_EPI = false, bool SP2 = false>
; __device__ __forceinline__ void gemm_phase(PG8_LAS unsigned char* lds, const Gemm g, const Sched& S, const Epi& E, const int tid) {
;     ...
;     const char* cA = (const char*)g.A + (size_t)cur.pm * tstep; const char* cB = (const char*)g.Bt + (size_t)cur.pn * tstep;
;     S.a_ready(cur);
;     if constexpr (SP2) {
;         PG8_STAGE(PG8_SB(0, 0), cB, voffB); PG8_STAGE(PG8_SB(0, 1), cB + hstepB, voffB); PG8_STAGE(PG8_SA(0, 0), cA, voffA); PG8_STAGE(PG8_SA(0, 1), cA + hstep, voffA);
;         if (wr == 1) PG8_BAR;
;         PG8_WAIT_V(2); PG8_BAR;
;         PG8_STAGE(PG8_SB(1, 0), cB + kstep, voffB); PG8_STAGE(PG8_SA(1, 0), cA + kstep, voffA); PG8_STAGE(PG8_SB(1, 1), cB + hstepB + kstep, voffB);
;         PG8_WAIT_V(6); PG8_BAR;
.LBB0_952:
	s_or_b64 exec, exec, s[0:1]
	v_readlane_b32 s0, v250, 2
	v_readlane_b32 s4, v250, 10
	v_readlane_b32 s1, v250, 3
	v_readlane_b32 s5, v250, 11
	s_and_b64 s[0:1], s[0:1], s[4:5]
	s_andn2_b64 vcc, exec, s[0:1]
	s_waitcnt vmcnt(0)
	s_barrier
	s_cbranch_vccnz .LBB0_967
	s_mov_b64 s[8:9], s[48:49]
	s_mov_b32 s1, s2
	v_mov_b32_e32 v3, v0
	s_ashr_i32 s0, s1, 3
	s_cmp_gt_i32 s0, 31
	v_readfirstlane_b32 s12, v3
	s_cbranch_scc1 .LBB0_967
	v_lshlrev_b32_e32 v6, 4, v3
	v_add_u32_e32 v7, 0x2000, v6
	v_ashrrev_i32_e32 v10, 31, v7
	v_lshrrev_b32_e32 v10, 22, v10
	v_add_u32_e32 v10, v7, v10
	v_ashrrev_i32_e32 v12, 10, v10
	v_mul_i32_i24_e32 v10, 0x400, v12
	v_sub_u32_e32 v7, v7, v10
	v_lshrrev_b32_e32 v10, 4, v7
	v_bitop3_b32 v7, v10, v7, 32 bitop3:0x6c
	v_ashrrev_i32_e32 v10, 31, v7
	v_lshrrev_b32_e32 v10, 26, v10
	v_add_u32_e32 v10, v7, v10
	v_lshlrev_b32_e32 v11, 3, v12
	v_ashrrev_i32_e32 v13, 6, v10
	v_and_b32_e32 v11, -16, v11
	v_add_u32_e32 v11, v13, v11
	v_lshrrev_b32_e32 v14, 2, v11
	v_lshlrev_b32_e32 v16, 1, v11
	v_and_b32_e32 v10, 0xc0, v10
	v_and_b32_e32 v14, 4, v14
	v_and_b32_e32 v15, 3, v13
	v_and_b32_e32 v16, 0x1fffd8, v16
	v_sub_u32_e32 v7, v7, v10
	v_or3_b32 v15, v15, v14, v16
	v_lshlrev_b32_e32 v14, 5, v12
	v_ashrrev_i16_sdwa v7, v205, sext(v7) dst_sel:DWORD dst_unused:UNUSED_PAD src0_sel:DWORD src1_sel:BYTE_0
	v_and_b32_e32 v16, 32, v14
	v_bfe_i32 v14, v7, 0, 16
	v_add_lshl_u32 v7, v16, v14, 1
	v_lshl_add_u32 v134, v15, 11, v7
	v_lshl_add_u32 v136, v11, 11, v7
	v_bfe_i32 v7, v3, 27, 1
	v_lshrrev_b32_e32 v7, 22, v7
	v_add_u32_e32 v7, v6, v7
	v_and_b32_e32 v7, 0xfffffc00, v7
	v_sub_u32_e32 v6, v6, v7
	v_lshrrev_b32_e32 v7, 4, v6
	v_ashrrev_i32_e32 v10, 31, v3
	v_bitop3_b32 v6, v7, v6, 32 bitop3:0x6c
	v_lshrrev_b32_e32 v10, 26, v10
	v_ashrrev_i32_e32 v7, 31, v6
	v_add_u32_e32 v10, v3, v10
	v_lshrrev_b32_e32 v7, 26, v7
	v_ashrrev_i32_e32 v16, 6, v10
	s_load_dwordx4 s[4:7], s[8:9], 0x108
	v_add_u32_e32 v7, v6, v7
	v_lshlrev_b32_e32 v10, 3, v16
	v_ashrrev_i32_e32 v15, 6, v7
	v_and_b32_e32 v10, -16, v10
	v_add_u32_e32 v10, v15, v10
	v_lshrrev_b32_e32 v11, 2, v10
	v_lshlrev_b32_e32 v18, 1, v10
	v_and_b32_e32 v7, 0xc0, v7
	v_and_b32_e32 v11, 4, v11
	v_and_b32_e32 v17, 3, v15
	v_and_b32_e32 v18, 0x1fffd8, v18
	v_sub_u32_e32 v6, v6, v7
	s_waitcnt lgkmcnt(0)
	v_mov_b32_e32 v133, s7
	v_mov_b32_e32 v132, s6
	s_mov_b64 s[6:7], 0xe700000
	v_or3_b32 v11, v17, v11, v18
	v_lshlrev_b32_e32 v17, 5, v16
	v_ashrrev_i16_sdwa v6, v205, sext(v6) dst_sel:DWORD dst_unused:UNUSED_PAD src0_sel:DWORD src1_sel:BYTE_0
	s_and_b32 s3, s1, 7
	v_lshl_add_u64 v[8:9], v[132:133], 0, s[6:7]
	s_mov_b64 s[6:7], 0x1100000
	s_ashr_i32 s14, s12, 6
	v_and_b32_e32 v18, 32, v17
	v_bfe_i32 v17, v6, 0, 16
	s_ashr_i32 s1, s0, 31
	v_lshl_add_u64 v[4:5], v[132:133], 0, s[6:7]
	s_lshl_b32 s27, s14, 10
	v_add_lshl_u32 v6, v18, v17, 1
	s_lshl_b64 s[6:7], s[0:1], 19
	v_lshl_add_u32 v138, v11, 11, v6
	v_lshl_add_u32 v140, v10, 11, v6
	v_lshl_add_u64 v[10:11], v[4:5], 0, s[6:7]
	s_add_i32 s1, s27, 0
	v_mov_b32_e32 v139, v2
	v_readfirstlane_b32 s24, v4
	v_readfirstlane_b32 s25, v5
	s_add_i32 m0, s1, 0x10000
	v_lshl_add_u64 v[4:5], v[10:11], 0, v[138:139]
	v_mov_b32_e32 v135, v2
	s_mov_b64 s[8:9], 0x10000
	v_readfirstlane_b32 s6, v10
	v_readfirstlane_b32 s7, v11
	global_load_lds_dwordx4 v[4:5], off
	v_lshl_add_u64 v[6:7], v[10:11], 0, v[134:135]
	s_add_i32 m0, s1, 0x12000
	v_lshl_add_u64 v[10:11], v[10:11], 0, s[8:9]
	s_lshl_b32 s34, s3, 19
	global_load_lds_dwordx4 v[6:7], off
	s_add_i32 m0, s1, 0x14000
	v_lshl_add_u64 v[18:19], v[10:11], 0, v[138:139]
	global_load_lds_dwordx4 v[18:19], off
	v_lshl_add_u64 v[10:11], v[10:11], 0, v[134:135]
	s_add_i32 m0, s1, 0x16000
	v_lshl_add_u64 v[18:19], v[8:9], 0, s[34:35]
	v_mov_b32_e32 v141, v2
	v_readfirstlane_b32 s22, v8
	v_readfirstlane_b32 s23, v9
	global_load_lds_dwordx4 v[10:11], off
	v_lshl_add_u64 v[8:9], v[18:19], 0, v[140:141]
	s_mov_b32 m0, s1
	v_mov_b32_e32 v137, v2
	s_add_i32 s28, s1, 0x2000
	v_readfirstlane_b32 s8, v18
	v_readfirstlane_b32 s9, v19
	global_load_lds_dwordx4 v[8:9], off
	v_lshl_add_u64 v[10:11], v[18:19], 0, v[136:137]
	s_mov_b32 m0, s28
	v_lshl_add_u64 v[18:19], v[18:19], 0, s[50:51]
	s_add_i32 s29, s1, 0x4000
	global_load_lds_dwordx4 v[10:11], off
	v_lshl_add_u64 v[20:21], v[18:19], 0, v[140:141]
	s_mov_b32 m0, s29
	s_add_i32 s30, s1, 0x6000
	global_load_lds_dwordx4 v[20:21], off
	v_lshl_add_u64 v[18:19], v[18:19], 0, v[136:137]
	s_mov_b32 m0, s30
	s_ashr_i32 s13, s12, 8
	global_load_lds_dwordx4 v[18:19], off
	s_cmp_eq_u32 s13, 1
	s_cselect_b64 s[10:11], -1, 0
	s_cmp_lg_u32 s13, 1
	s_cbranch_scc1 .LBB0_956
	s_barrier

; __device__ __forceinline__ void grp_barrier(const XcdBarrier& b, unsigned gsz) {
;     asm volatile("s_waitcnt vmcnt(0)" ::: "memory");
;     __syncthreads();
.LBB0_1022:
	s_or_b64 exec, exec, s[4:5]
	s_mov_b64 s[4:5], s[48:49]
	s_mov_b32 s6, s2
	s_getreg_b32 s3, hwreg(HW_REG_XCC_ID, 0, 4)
	s_waitcnt vmcnt(0)
	v_readfirstlane_b32 s0, v0
	s_nop 3
	s_lshr_b32 s0, s0, 6
	s_cmp_eq_u32 s0, 1
	s_cbranch_scc0 .Lgb_noinv6
	buffer_inv sc1

; #define PG8_STAGE(bufoff, gbase, voff) do { _Pragma("unroll") for (int _i = 0; _i < 2; ++_i) \
;         __builtin_amdgcn_global_load_lds((const unsigned*)((const char*)(gbase) + (voff)[_i]), (PG8_LAS unsigned*)(lds + (bufoff) + ldsw + _i * 8192), 16, 0, 0); } while (0)
; #define PG8_WAIT_V(n) asm volatile("s_waitcnt vmcnt(" #n ")" ::: "memory")
; #define PG8_BAR __builtin_amdgcn_s_barrier()
; template <class Epi, class Sched, bool ALIGN_EPI = false, bool SP2 = false>
; __device__ __forceinline__ void gemm_phase(PG8_LAS unsigned char* lds, const Gemm g, const Sched& S, const Epi& E, const int tid) {
;     ...
;     const char* cA = (const char*)g.A + (size_t)cur.pm * tstep; const char* cB = (const char*)g.Bt + (size_t)cur.pn * tstep;
;     S.a_ready(cur);
;     if constexpr (SP2) {
;         PG8_STAGE(PG8_SB(0, 0), cB, voffB); PG8_STAGE(PG8_SB(0, 1), cB + hstepB, voffB); PG8_STAGE(PG8_SA(0, 0), cA, voffA); PG8_STAGE(PG8_SA(0, 1), cA + hstep, voffA);
;         if (wr == 1) PG8_BAR;
;         PG8_WAIT_V(2); PG8_BAR;
;         PG8_STAGE(PG8_SB(1, 0), cB + kstep, voffB); PG8_STAGE(PG8_SA(1, 0), cA + kstep, voffA); PG8_STAGE(PG8_SB(1, 1), cB + hstepB + kstep, voffB);
;         PG8_WAIT_V(6); PG8_BAR;
.LBB0_1082:
	s_or_b64 exec, exec, s[0:1]
	s_cmp_lg_u32 s46, 0
	v_readlane_b32 s4, v250, 6
	s_cselect_b64 s[0:1], -1, 0
	v_readlane_b32 s5, v250, 7
	s_or_b64 s[0:1], s[4:5], s[0:1]
	s_and_b64 vcc, exec, s[0:1]
	s_waitcnt vmcnt(0)
	s_barrier
	s_cbranch_vccnz .LBB0_1097
	v_mov_b32_e32 v3, v0
	s_mov_b64 s[8:9], s[48:49]
	s_mov_b32 s1, s2
	s_ashr_i32 s0, s1, 3
	s_cmp_gt_i32 s0, 31
	v_readfirstlane_b32 s12, v3
	s_cbranch_scc1 .LBB0_1097
	v_lshlrev_b32_e32 v6, 4, v3
	v_add_u32_e32 v7, 0x2000, v6
	v_ashrrev_i32_e32 v10, 31, v7
	v_lshrrev_b32_e32 v10, 22, v10
	v_add_u32_e32 v10, v7, v10
	v_ashrrev_i32_e32 v12, 10, v10
	v_mul_i32_i24_e32 v10, 0x400, v12
	v_sub_u32_e32 v7, v7, v10
	v_lshrrev_b32_e32 v10, 4, v7
	v_bitop3_b32 v7, v10, v7, 32 bitop3:0x6c
	v_ashrrev_i32_e32 v10, 31, v7
	v_lshrrev_b32_e32 v10, 26, v10
	v_add_u32_e32 v10, v7, v10
	v_lshlrev_b32_e32 v11, 3, v12
	v_ashrrev_i32_e32 v13, 6, v10
	v_and_b32_e32 v11, -16, v11
	v_add_u32_e32 v11, v13, v11
	v_lshrrev_b32_e32 v14, 2, v11
	v_lshlrev_b32_e32 v16, 1, v11
	v_and_b32_e32 v10, 0xc0, v10
	v_and_b32_e32 v14, 4, v14
	v_and_b32_e32 v15, 3, v13
	v_and_b32_e32 v16, 0x1fffd8, v16
	v_sub_u32_e32 v7, v7, v10
	v_or3_b32 v15, v15, v14, v16
	v_lshlrev_b32_e32 v14, 5, v12
	v_ashrrev_i16_sdwa v7, v205, sext(v7) dst_sel:DWORD dst_unused:UNUSED_PAD src0_sel:DWORD src1_sel:BYTE_0
	v_and_b32_e32 v16, 32, v14
	v_bfe_i32 v14, v7, 0, 16
	v_add_lshl_u32 v7, v16, v14, 1
	v_lshl_add_u32 v134, v15, 11, v7
	v_lshl_add_u32 v136, v11, 11, v7
	v_bfe_i32 v7, v3, 27, 1
	v_lshrrev_b32_e32 v7, 22, v7
	v_add_u32_e32 v7, v6, v7
	v_and_b32_e32 v7, 0xfffffc00, v7
	v_sub_u32_e32 v6, v6, v7
	v_lshrrev_b32_e32 v7, 4, v6
	v_ashrrev_i32_e32 v10, 31, v3
	v_bitop3_b32 v6, v7, v6, 32 bitop3:0x6c
	v_lshrrev_b32_e32 v10, 26, v10
	v_ashrrev_i32_e32 v7, 31, v6
	v_add_u32_e32 v10, v3, v10
	v_lshrrev_b32_e32 v7, 26, v7
	v_ashrrev_i32_e32 v16, 6, v10
	s_load_dwordx4 s[4:7], s[8:9], 0x108
	v_add_u32_e32 v7, v6, v7
	v_lshlrev_b32_e32 v10, 3, v16
	v_ashrrev_i32_e32 v15, 6, v7
	v_and_b32_e32 v10, -16, v10
	v_add_u32_e32 v10, v15, v10
	v_lshrrev_b32_e32 v11, 2, v10
	v_lshlrev_b32_e32 v18, 1, v10
	v_and_b32_e32 v7, 0xc0, v7
	v_and_b32_e32 v11, 4, v11
	v_and_b32_e32 v17, 3, v15
	v_and_b32_e32 v18, 0x1fffd8, v18
	v_sub_u32_e32 v6, v6, v7
	s_waitcnt lgkmcnt(0)
	v_mov_b32_e32 v133, s7
	v_mov_b32_e32 v132, s6
	s_mov_b64 s[6:7], 0xe700000
	v_or3_b32 v11, v17, v11, v18
	v_lshlrev_b32_e32 v17, 5, v16
	v_ashrrev_i16_sdwa v6, v205, sext(v6) dst_sel:DWORD dst_unused:UNUSED_PAD src0_sel:DWORD src1_sel:BYTE_0
	s_and_b32 s3, s1, 7
	v_lshl_add_u64 v[8:9], v[132:133], 0, s[6:7]
	s_mov_b64 s[6:7], 0x1100000
	s_ashr_i32 s14, s12, 6
	v_and_b32_e32 v18, 32, v17
	v_bfe_i32 v17, v6, 0, 16
	s_ashr_i32 s1, s0, 31
	v_lshl_add_u64 v[4:5], v[132:133], 0, s[6:7]
	s_lshl_b32 s27, s14, 10
	v_add_lshl_u32 v6, v18, v17, 1
	s_lshl_b64 s[6:7], s[0:1], 19
	v_lshl_add_u32 v138, v11, 11, v6
	v_lshl_add_u32 v140, v10, 11, v6
	v_lshl_add_u64 v[10:11], v[4:5], 0, s[6:7]
	s_add_i32 s1, s27, 0
	v_mov_b32_e32 v139, v2
	v_readfirstlane_b32 s24, v4
	v_readfirstlane_b32 s25, v5
	s_add_i32 m0, s1, 0x10000
	v_lshl_add_u64 v[4:5], v[10:11], 0, v[138:139]
	v_mov_b32_e32 v135, v2
	s_mov_b64 s[8:9], 0x10000
	v_readfirstlane_b32 s6, v10
	v_readfirstlane_b32 s7, v11
	global_load_lds_dwordx4 v[4:5], off
	v_lshl_add_u64 v[6:7], v[10:11], 0, v[134:135]
	s_add_i32 m0, s1, 0x12000
	v_lshl_add_u64 v[10:11], v[10:11], 0, s[8:9]
	s_lshl_b32 s34, s3, 19
	global_load_lds_dwordx4 v[6:7], off
	s_add_i32 m0, s1, 0x14000
	v_lshl_add_u64 v[18:19], v[10:11], 0, v[138:139]
	global_load_lds_dwordx4 v[18:19], off
	v_lshl_add_u64 v[10:11], v[10:11], 0, v[134:135]
	s_add_i32 m0, s1, 0x16000
	v_lshl_add_u64 v[18:19], v[8:9], 0, s[34:35]
	v_mov_b32_e32 v141, v2
	v_readfirstlane_b32 s22, v8
	v_readfirstlane_b32 s23, v9
	global_load_lds_dwordx4 v[10:11], off
	v_lshl_add_u64 v[8:9], v[18:19], 0, v[140:141]
	s_mov_b32 m0, s1
	v_mov_b32_e32 v137, v2
	s_add_i32 s28, s1, 0x2000
	v_readfirstlane_b32 s8, v18
	v_readfirstlane_b32 s9, v19
	global_load_lds_dwordx4 v[8:9], off
	v_lshl_add_u64 v[10:11], v[18:19], 0, v[136:137]
	s_mov_b32 m0, s28
	v_lshl_add_u64 v[18:19], v[18:19], 0, s[50:51]
	s_add_i32 s29, s1, 0x4000
	global_load_lds_dwordx4 v[10:11], off
	v_lshl_add_u64 v[20:21], v[18:19], 0, v[140:141]
	s_mov_b32 m0, s29
	s_add_i32 s30, s1, 0x6000
	global_load_lds_dwordx4 v[20:21], off
	v_lshl_add_u64 v[18:19], v[18:19], 0, v[136:137]
	s_mov_b32 m0, s30
	s_ashr_i32 s13, s12, 8
	global_load_lds_dwordx4 v[18:19], off
	s_cmp_eq_u32 s13, 1
	s_cselect_b64 s[10:11], -1, 0
	s_cmp_lg_u32 s13, 1
	s_cbranch_scc1 .LBB0_1086
	s_barrier

; __device__ __forceinline__ void grp_barrier(const XcdBarrier& b, unsigned gsz) {
;     asm volatile("s_waitcnt vmcnt(0)" ::: "memory");
;     __syncthreads();
.LBB0_1119:
	s_mov_b64 s[4:5], s[48:49]
	s_mov_b32 s10, s2
	s_getreg_b32 s3, hwreg(HW_REG_XCC_ID, 0, 4)
	s_waitcnt vmcnt(0)
	s_waitcnt lgkmcnt(0)
	v_readfirstlane_b32 s0, v0
	s_nop 3
	s_lshr_b32 s0, s0, 6
	s_cmp_eq_u32 s0, 1
	s_cbranch_scc0 .Lgb_noinv7
	buffer_inv sc1

; __device__ __forceinline__ unsigned xb_ld(unsigned* p)              { return __hip_atomic_load(p, __ATOMIC_RELAXED, __HIP_MEMORY_SCOPE_AGENT); }
; __device__ __forceinline__ unsigned xb_add(unsigned* p, unsigned v) { return __hip_atomic_fetch_add(p, v, __ATOMIC_RELAXED, __HIP_MEMORY_SCOPE_AGENT); }
; #define XB_SPIN(cond, bar) do { unsigned _sp = 0; while (cond) { __builtin_amdgcn_s_sleep(1); \
;     if ((++_sp & 255u) == 0u) { if (xb_ld(&(bar)[XB_TMO])) break; if (_sp > XB_SPIN_CAP) { atomicAdd(&(bar)[XB_TMO], 1u); break; } } } } while (0)
; __device__ __forceinline__ void grp_barrier(const XcdBarrier& b, unsigned gsz) {
;     ...
;         const unsigned old = xb_add(&bar[XB_XSUB(b.x)], 1u);
;         const bool early = (nx == 1u);
;         if (early) __builtin_amdgcn_fence(__ATOMIC_ACQUIRE, "agent");
;         const unsigned gen = old / nloc;
;         if (old + 1u == (gen + 1u) * nloc) {
;             if (nx > 1u) __builtin_amdgcn_fence(__ATOMIC_RELEASE, "agent");
;             if (!early) asm volatile("s_waitcnt vmcnt(0)" ::: "memory");
;             if (!early) {
;             const unsigned og = xb_add(&bar[XB_TOP], 1u);
;             const unsigned tg = og / nx;
;             if (og + 1u == (tg + 1u) * nx) xb_add(&bar[XB_TOPGEN], 1u);
;             else XB_SPIN(xb_ld(&bar[XB_TOPGEN]) == tg, bar);
;             }
;             if (!early) __builtin_amdgcn_fence(__ATOMIC_ACQUIRE, "agent");
;             xb_add(&bar[XB_XGEN(b.x)], 1u);
;             asm volatile("s_waitcnt vmcnt(0)" ::: "memory");
;         } else {
;             XB_SPIN(xb_ld(&bar[XB_XGEN(b.x)]) == gen, bar);
.LBB0_1137:
	s_or_b64 exec, exec, s[16:17]
	s_waitcnt lgkmcnt(0)
	v_cmp_eq_u32_e32 vcc, 1, v4
	s_cbranch_vccz .Lgb_slow7
	global_load_dword v7, v202, s[12:13] offset:1024 sc1
	s_mov_b32 s3, 0
	s_waitcnt vmcnt(1)
	v_and_b32_e32 v3, 31, v6
	v_and_b32_e32 v6, 0xffffffe0, v6
	v_cmp_eq_u32_e32 vcc, 31, v3
	v_add_u32_e32 v6, 32, v6
	s_cbranch_vccz .Lgb_poll7
	global_atomic_add v203, v205, s[12:13] offset:1024
	s_branch .Lgb_done7
.Lgb_poll7:
	s_waitcnt vmcnt(0)
	v_sub_u32_e32 v3, v7, v6
	v_cmp_gt_i32_e32 vcc, 0, v3
	s_cbranch_vccz .Lgb_done7
	s_sleep 1
	s_add_u32 s3, s3, 1
	s_cmp_lt_u32 s3, 0x40000
	s_cbranch_scc0 .Lgb_done7
	global_load_dword v7, v202, s[12:13] offset:1024 sc1
	s_branch .Lgb_poll7

; #define LAS __attribute__((address_space(3)))
; DI unsigned pk2(float lo, float hi) { f32x2 v = {lo, hi}; return __builtin_bit_cast(unsigned, __builtin_convertvector(v, bf2_t)); }
; DI void attn_sample_unit(LAS unsigned char* lds, const bf16* Q, const float* CK, const float* CV, bf16* AO, int su, int tid, int wave, int lane) {
;     const int pair = wave >> 2, mq = wave & 3, bh = su * 2 + pair, b = bh >> 2, h = bh & 3;
;     LAS unsigned char* wl = lds + wave * 16896;
;     const int r = lane & 31, hh = lane >> 5;
;     bf16x8 bq[16];
;     {   const bf16* qrow = Q + (size_t)(MP + b * 8 + (r & 7)) * DM + h * 256 + 8 * hh;
; #pragma unroll
;         for (int kk = 0; kk < 16; ++kk) { bf16x8 v = *(const bf16x8*)(qrow + 16 * kk); if (r >= 8) { v = (bf16x8){0, 0, 0, 0, 0, 0, 0, 0}; } bq[kk] = v; } }
;     const float* kb = CK + ((size_t)(b * 256 + 64 * mq) * 4 + h) * 256 + 4 * lane;
;     f32x16 acc[2];
;     const float* vb = CV + ((size_t)(b * 256 + 64 * mq) * 4 + h) * 256 + 4 * lane;
;     f32x4 v[16];
; #pragma unroll
;     for (int i = 0; i < 16; ++i) v[i] = __builtin_nontemporal_load((const f32x4*)(kb + (size_t)i * 1024));
; #pragma unroll
;     for (int c = 0; c < 2; ++c) {
; #pragma unroll
;         for (int hf = 0; hf < 2; ++hf) {
; #pragma unroll
;             for (int i = 0; i < 16; ++i) { u32x2 w; w.x = pk2(v[i][0], v[i][1]); w.y = pk2(v[i][2], v[i][3]); *(LAS u32x2*)(wl + (16 * hf + i) * KV_PITCH + lane * 8) = w; }
.LBB0_1179:
	s_or_b64 exec, exec, s[0:1]
	s_mov_b64 s[10:11], s[48:49]
	s_mov_b32 s24, s2
	v_mov_b32_e32 v3, v0
	s_waitcnt vmcnt(0)
	s_barrier
	s_load_dwordx2 s[16:17], s[10:11], 0x110
	s_and_b32 s22, s24, 7
	s_ashr_i32 s23, s24, 3
	s_and_b32 s0, s24, 1
	s_cmp_eq_u32 s0, 0
	s_cselect_b64 s[12:13], -1, 0
	s_cmp_eq_u32 s0, 1
	s_cselect_b64 s[18:19], -1, 0
	s_and_b64 vcc, exec, s[12:13]
	s_cbranch_vccnz .LBB0_1185
	v_mov_b32_e32 v22, v3
	s_load_dwordx4 s[28:31], s[10:11], 0x30
	v_readfirstlane_b32 s3, v22
	s_ashr_i32 s1, s3, 6
	s_lshl_b64 s[4:5], s[6:7], 27
	v_and_b32_e32 v166, 63, v22
	s_waitcnt lgkmcnt(0)
	s_add_u32 s20, s28, s4
	s_addc_u32 s21, s29, s5
	s_add_u32 s27, s30, s4
	s_addc_u32 s28, s31, s5
	s_lshl_b32 s4, s22, 6
	s_lshl_b32 s5, s23, 1
	s_ashr_i32 s0, s3, 8
	s_add_i32 s4, s4, s5
	s_add_i32 s4, s4, s0
	s_ashr_i32 s5, s4, 2
	s_lshl_b32 s4, s4, 8
	s_and_b32 s30, s4, 0x300
	s_lshl_b32 s4, s5, 8
	s_and_b32 s25, s3, 0xc0
	s_or_b32 s4, s4, s25
	s_lshl_b32 s0, s5, 3
	s_ashr_i32 s5, s4, 31
	s_lshl_b64 s[4:5], s[4:5], 12
	s_lshl_b32 s3, s30, 2
	s_addk_i32 s0, 0x4000
	s_lshl_b32 s34, s30, 1
	s_or_b32 s3, s4, s3
	s_add_u32 s20, s20, s3
	s_addc_u32 s21, s21, s5
	v_lshlrev_b32_e32 v80, 4, v166
	v_mov_b32_e32 v81, v2
	v_lshl_add_u64 v[82:83], s[20:21], 0, v[80:81]
	v_add_co_u32_e32 v12, vcc, s33, v82
	global_load_dwordx4 v[4:7], v80, s[20:21] nt
	s_nop 0
	v_addc_co_u32_e32 v13, vcc, 0, v83, vcc
	v_add_co_u32_e32 v20, vcc, s44, v82
	global_load_dwordx4 v[8:11], v[12:13], off offset:-4096 nt
	s_nop 0
	global_load_dwordx4 v[12:15], v[12:13], off nt
	v_addc_co_u32_e32 v21, vcc, 0, v83, vcc
	global_load_dwordx4 v[16:19], v[20:21], off offset:-4096 nt
	global_load_dwordx4 v[48:51], v[20:21], off nt
	v_and_or_b32 v20, v22, 7, s0
	v_ashrrev_i32_e32 v21, 31, v20
	v_lshlrev_b64 v[20:21], 11, v[20:21]
	v_bfe_u32 v121, v22, 5, 1
	v_lshl_add_u64 v[20:21], s[16:17], 0, v[20:21]
	v_lshl_add_u64 v[20:21], v[20:21], 0, s[34:35]
	v_lshlrev_b32_e32 v122, 4, v121
	v_mov_b32_e32 v123, v2
	v_lshl_add_u64 v[20:21], v[20:21], 0, v[122:123]
	s_mov_b64 s[20:21], 0x10b00000
	s_mov_b32 s4, 0x10b00000
	v_lshl_add_u64 v[164:165], v[20:21], 0, s[20:21]
	v_add_co_u32_e32 v20, vcc, s4, v20
	s_add_u32 s20, s27, s3
	s_nop 0
	v_addc_co_u32_e32 v21, vcc, 0, v21, vcc
	s_movk_i32 s27, 0x6000
	v_add_co_u32_e32 v72, vcc, s27, v82
	s_mov_b32 s30, 0x8000
	s_nop 0
	v_addc_co_u32_e32 v73, vcc, 0, v83, vcc
	v_add_co_u32_e32 v92, vcc, s30, v82
	s_mov_b32 s31, 0xa000
	s_nop 0
	v_addc_co_u32_e32 v93, vcc, 0, v83, vcc
	v_add_co_u32_e32 v100, vcc, s31, v82
	s_mov_b32 s36, 0xc000
	s_nop 0
	v_addc_co_u32_e32 v101, vcc, 0, v83, vcc
	v_add_co_u32_e32 v108, vcc, s36, v82
	s_mul_i32 s29, s1, 0x4200
	s_nop 0
	v_addc_co_u32_e32 v109, vcc, 0, v83, vcc
	s_mov_b32 s37, 0xe000
	s_addc_u32 s21, s28, s5
	v_add_co_u32_e32 v116, vcc, s37, v82
	s_add_i32 s28, s29, 0
	v_lshlrev_b32_e32 v123, 3, v166
	v_addc_co_u32_e32 v117, vcc, 0, v83, vcc
	s_mov_b32 s3, 0x10000
	v_add_u32_e32 v167, s28, v123
	v_and_b32_e32 v120, 31, v22
	global_load_dwordx4 v[52:55], v[20:21], off
	global_load_dwordx4 v[56:59], v[164:165], off offset:32
	global_load_dwordx4 v[60:63], v[164:165], off offset:64
	global_load_dwordx4 v[64:67], v[164:165], off offset:96
	global_load_dwordx4 v[84:87], v[164:165], off offset:128
	global_load_dwordx4 v[88:91], v[164:165], off offset:160
	global_load_dwordx4 v[44:47], v[164:165], off offset:192
	global_load_dwordx4 v[40:43], v[164:165], off offset:224
	global_load_dwordx4 v[36:39], v[164:165], off offset:256
	global_load_dwordx4 v[32:35], v[164:165], off offset:288
	global_load_dwordx4 v[28:31], v[164:165], off offset:320
	global_load_dwordx4 v[24:27], v[164:165], off offset:352
	global_load_dwordx4 v[20:23], v[164:165], off offset:384
	global_load_dwordx4 v[68:71], v[72:73], off offset:-4096 nt
	s_nop 0
	global_load_dwordx4 v[72:75], v[72:73], off nt
	s_nop 0
	global_load_dwordx4 v[76:79], v[92:93], off offset:-4096 nt
	s_nop 0
	global_load_dwordx4 v[92:95], v[92:93], off nt
	s_nop 0
	global_load_dwordx4 v[96:99], v[100:101], off offset:-4096 nt
	s_nop 0
	global_load_dwordx4 v[100:103], v[100:101], off nt
	s_nop 0
	global_load_dwordx4 v[104:107], v[108:109], off offset:-4096 nt
	s_nop 0
	global_load_dwordx4 v[108:111], v[108:109], off nt
	s_nop 0
	global_load_dwordx4 v[112:115], v[116:117], off offset:-4096 nt
	s_nop 0
	global_load_dwordx4 v[116:119], v[116:117], off nt
	v_add_co_u32_e32 v124, vcc, s3, v82
	s_mov_b32 s3, 0x12000
	s_nop 0
	v_addc_co_u32_e32 v125, vcc, 0, v83, vcc
	v_mul_u32_u24_e32 v123, 0x210, v120
	v_add3_u32 v122, s28, v123, v122
	s_waitcnt vmcnt(27)
	v_cvt_pk_bf16_f32 v4, v4, v5
	v_cvt_pk_bf16_f32 v5, v6, v7
	ds_write_b64 v167, v[4:5]
	s_waitcnt vmcnt(26)
	v_cvt_pk_bf16_f32 v4, v8, v9
	v_cvt_pk_bf16_f32 v5, v10, v11
	ds_write_b64 v167, v[4:5] offset:528
	s_waitcnt vmcnt(25)
	v_cvt_pk_bf16_f32 v4, v12, v13
	v_cvt_pk_bf16_f32 v5, v14, v15
	ds_write_b64 v167, v[4:5] offset:1056
	s_waitcnt vmcnt(24)
	v_cvt_pk_bf16_f32 v4, v16, v17
	v_cvt_pk_bf16_f32 v5, v18, v19
	v_add_co_u32_e32 v16, vcc, s3, v82
	ds_write_b64 v167, v[4:5] offset:1584
	s_nop 0
	v_addc_co_u32_e32 v17, vcc, 0, v83, vcc
	s_mov_b32 s3, 0x14000
	global_load_dwordx4 v[4:7], v[124:125], off offset:-4096 nt
	global_load_dwordx4 v[8:11], v[124:125], off nt
	v_add_co_u32_e32 v124, vcc, s3, v82
	s_mov_b32 s3, 0x16000
	s_nop 0
	v_addc_co_u32_e32 v125, vcc, 0, v83, vcc
	global_load_dwordx4 v[12:15], v[16:17], off offset:-4096
	s_nop 0
	global_load_dwordx4 v[16:19], v[16:17], off
	v_add_co_u32_e32 v132, vcc, s3, v82
	s_mov_b32 s3, 0x18000
	s_nop 0
	v_addc_co_u32_e32 v133, vcc, 0, v83, vcc
	s_waitcnt vmcnt(27)
; #define LAS __attribute__((address_space(3)))
; DI unsigned pk2(float lo, float hi) { f32x2 v = {lo, hi}; return __builtin_bit_cast(unsigned, __builtin_convertvector(v, bf2_t)); }
; DI f32x16 mfma32(bf16x8 a, bf16x8 b, f32x16 c) { return __builtin_amdgcn_mfma_f32_32x32x16_bf16(a, b, c, 0, 0, 0); }
; DI void attn_sample_unit(LAS unsigned char* lds, const bf16* Q, const float* CK, const float* CV, bf16* AO, int su, int tid, int wave, int lane) {
;     ...
;     for (int i = 0; i < 16; ++i) v[i] = __builtin_nontemporal_load((const f32x4*)(kb + (size_t)i * 1024));
; #pragma unroll
;     for (int c = 0; c < 2; ++c) {
; #pragma unroll
;         for (int hf = 0; hf < 2; ++hf) {
; #pragma unroll
;             for (int i = 0; i < 16; ++i) { u32x2 w; w.x = pk2(v[i][0], v[i][1]); w.y = pk2(v[i][2], v[i][3]); *(LAS u32x2*)(wl + (16 * hf + i) * KV_PITCH + lane * 8) = w; }
;             const int nb = 2 * c + hf + 1;
; #pragma unroll
;             for (int i = 0; i < 16; ++i) v[i] = __builtin_nontemporal_load(nb < 4 ? (const f32x4*)(kb + (size_t)(16 * nb + i) * 1024) : (const f32x4*)(vb + (size_t)i * 1024));
;         }
;         f32x16 a_ = zero16();
; #pragma unroll
;         for (int kk = 0; kk < 16; ++kk) { const bf16x8 a = *(const LAS bf16x8*)(wl + r * KV_PITCH + (16 * kk + 8 * hh) * 2); a_ = mfma32(a, bq[kk], a_); }
;         acc[c] = a_;
	v_cvt_pk_bf16_f32 v170, v48, v49
	v_cvt_pk_bf16_f32 v171, v50, v51
	global_load_dwordx4 v[48:51], v[124:125], off offset:-4096
	s_nop 0
	global_load_dwordx4 v[124:127], v[124:125], off
	v_add_co_u32_e32 v140, vcc, s3, v82
	s_mov_b32 s3, 0x1a000
	s_nop 0
	v_addc_co_u32_e32 v141, vcc, 0, v83, vcc
	global_load_dwordx4 v[128:131], v[132:133], off offset:-4096
	s_nop 0
	global_load_dwordx4 v[132:135], v[132:133], off
	v_add_co_u32_e32 v148, vcc, s3, v82
	s_mov_b32 s3, 0x1c000
	s_nop 0
	v_addc_co_u32_e32 v149, vcc, 0, v83, vcc
	global_load_dwordx4 v[136:139], v[140:141], off offset:-4096
	s_nop 0
	global_load_dwordx4 v[140:143], v[140:141], off
	v_add_co_u32_e32 v156, vcc, s3, v82
	s_mov_b32 s3, 0x1e000
	s_nop 0
	v_addc_co_u32_e32 v157, vcc, 0, v83, vcc
	global_load_dwordx4 v[144:147], v[148:149], off offset:-4096
	s_nop 0
	global_load_dwordx4 v[148:151], v[148:149], off
	v_add_co_u32_e32 v172, vcc, s3, v82
	s_mov_b32 s3, 0x20000
	s_nop 0
	v_addc_co_u32_e32 v173, vcc, 0, v83, vcc
	global_load_dwordx4 v[152:155], v[156:157], off offset:-4096
	s_nop 0
	global_load_dwordx4 v[156:159], v[156:157], off
	v_add_co_u32_e32 v178, vcc, s3, v82
	global_load_dwordx4 v[160:163], v[172:173], off offset:-4096
	s_nop 0
	v_addc_co_u32_e32 v179, vcc, 0, v83, vcc
	ds_write_b64 v167, v[170:171] offset:2112
	global_load_dwordx4 v[174:177], v[178:179], off offset:-4096
	s_waitcnt vmcnt(25)
	v_cvt_pk_bf16_f32 v68, v68, v69
	global_load_dwordx4 v[170:173], v[172:173], off
	v_cvt_pk_bf16_f32 v69, v70, v71
	ds_write_b64 v167, v[68:69] offset:2640
	s_waitcnt vmcnt(25)
	v_cvt_pk_bf16_f32 v68, v72, v73
	v_cvt_pk_bf16_f32 v69, v74, v75
	ds_write_b64 v167, v[68:69] offset:3168
	s_waitcnt vmcnt(24)
	v_cvt_pk_bf16_f32 v68, v76, v77
	v_cvt_pk_bf16_f32 v69, v78, v79
	ds_write_b64 v167, v[68:69] offset:3696
	s_waitcnt vmcnt(23)
	v_cvt_pk_bf16_f32 v68, v92, v93
	v_cvt_pk_bf16_f32 v69, v94, v95
	ds_write_b64 v167, v[68:69] offset:4224
	s_waitcnt vmcnt(22)
	v_cvt_pk_bf16_f32 v68, v96, v97
	v_cvt_pk_bf16_f32 v69, v98, v99
	ds_write_b64 v167, v[68:69] offset:4752
	s_waitcnt vmcnt(21)
	v_cvt_pk_bf16_f32 v68, v100, v101
	v_cvt_pk_bf16_f32 v69, v102, v103
	ds_write_b64 v167, v[68:69] offset:5280
	s_waitcnt vmcnt(20)
	v_cvt_pk_bf16_f32 v68, v104, v105
	v_cvt_pk_bf16_f32 v69, v106, v107
	ds_write_b64 v167, v[68:69] offset:5808
	s_waitcnt vmcnt(19)
	v_cvt_pk_bf16_f32 v68, v108, v109
	v_cvt_pk_bf16_f32 v69, v110, v111
	ds_write_b64 v167, v[68:69] offset:6336
	s_waitcnt vmcnt(18)
	v_cvt_pk_bf16_f32 v68, v112, v113
	v_cvt_pk_bf16_f32 v69, v114, v115
	global_load_dwordx4 v[92:95], v[178:179], off
	ds_write_b64 v167, v[68:69] offset:6864
	s_waitcnt vmcnt(18)
	v_cvt_pk_bf16_f32 v68, v116, v117
	v_cvt_pk_bf16_f32 v69, v118, v119
	ds_write_b64 v167, v[68:69] offset:7392
	v_cmp_lt_u32_e32 vcc, 7, v120
	s_waitcnt vmcnt(17)
	v_cvt_pk_bf16_f32 v4, v4, v5
	v_cvt_pk_bf16_f32 v5, v6, v7
	ds_write_b64 v167, v[4:5] offset:7920
	s_waitcnt vmcnt(16)
	v_cvt_pk_bf16_f32 v4, v8, v9
	v_cvt_pk_bf16_f32 v5, v10, v11
	ds_write_b64 v167, v[4:5] offset:8448
	s_waitcnt vmcnt(15)
	v_cvt_pk_bf16_f32 v4, v12, v13
	v_cvt_pk_bf16_f32 v5, v14, v15
	ds_write_b64 v167, v[4:5] offset:8976
	s_waitcnt vmcnt(14)
	v_cvt_pk_bf16_f32 v4, v16, v17
	v_cvt_pk_bf16_f32 v5, v18, v19
	ds_write_b64 v167, v[4:5] offset:9504
	v_cndmask_b32_e64 v71, v55, 0, vcc
	v_cndmask_b32_e64 v70, v54, 0, vcc
	s_waitcnt vmcnt(13)
	v_cvt_pk_bf16_f32 v4, v48, v49
	v_cvt_pk_bf16_f32 v5, v50, v51
	ds_write_b64 v167, v[4:5] offset:10032
	s_waitcnt vmcnt(12)
	v_cvt_pk_bf16_f32 v4, v124, v125
	v_cvt_pk_bf16_f32 v5, v126, v127
	ds_write_b64 v167, v[4:5] offset:10560
	s_waitcnt vmcnt(11)
	v_cvt_pk_bf16_f32 v4, v128, v129
	v_cvt_pk_bf16_f32 v5, v130, v131
	ds_write_b64 v167, v[4:5] offset:11088
	s_waitcnt vmcnt(10)
	v_cvt_pk_bf16_f32 v4, v132, v133
	v_cvt_pk_bf16_f32 v5, v134, v135
	ds_write_b64 v167, v[4:5] offset:11616
	s_waitcnt vmcnt(9)
	v_cvt_pk_bf16_f32 v4, v136, v137
	v_cvt_pk_bf16_f32 v5, v138, v139
	ds_write_b64 v167, v[4:5] offset:12144
	s_waitcnt vmcnt(8)
	v_cvt_pk_bf16_f32 v4, v140, v141
	v_cvt_pk_bf16_f32 v5, v142, v143
	ds_write_b64 v167, v[4:5] offset:12672
	s_waitcnt vmcnt(7)
	v_cvt_pk_bf16_f32 v4, v144, v145
	v_cvt_pk_bf16_f32 v5, v146, v147
	ds_write_b64 v167, v[4:5] offset:13200
	s_waitcnt vmcnt(6)
	v_cvt_pk_bf16_f32 v4, v148, v149
	v_cvt_pk_bf16_f32 v5, v150, v151
	ds_write_b64 v167, v[4:5] offset:13728
	s_waitcnt vmcnt(5)
	v_cvt_pk_bf16_f32 v4, v152, v153
	v_cvt_pk_bf16_f32 v5, v154, v155
	ds_write_b64 v167, v[4:5] offset:14256
	s_waitcnt vmcnt(4)
	v_cvt_pk_bf16_f32 v4, v156, v157
	v_cvt_pk_bf16_f32 v5, v158, v159
	ds_write_b64 v167, v[4:5] offset:14784
	s_waitcnt vmcnt(3)
	v_cvt_pk_bf16_f32 v4, v160, v161
	v_cvt_pk_bf16_f32 v5, v162, v163
	ds_write_b64 v167, v[4:5] offset:15312
	v_cndmask_b32_e64 v69, v53, 0, vcc
	s_waitcnt vmcnt(1)
	v_cvt_pk_bf16_f32 v4, v170, v171
	v_cvt_pk_bf16_f32 v5, v172, v173
	ds_write_b64 v167, v[4:5] offset:15840
	v_cvt_pk_bf16_f32 v4, v174, v175
	v_cvt_pk_bf16_f32 v5, v176, v177
	ds_write_b64 v167, v[4:5] offset:16368
	ds_read_b128 v[4:7], v122
	global_load_dwordx4 v[96:99], v[164:165], off offset:416
	global_load_dwordx4 v[100:103], v[164:165], off offset:448
	global_load_dwordx4 v[104:107], v[164:165], off offset:480
	v_cndmask_b32_e64 v68, v52, 0, vcc
	ds_read_b128 v[48:51], v122 offset:32
	ds_read_b128 v[52:55], v122 offset:64
	s_waitcnt lgkmcnt(2)
	v_mfma_f32_32x32x16_bf16 v[4:19], v[4:7], v[68:71], 0
	v_cndmask_b32_e64 v75, v59, 0, vcc
	v_cndmask_b32_e64 v74, v58, 0, vcc
	v_cndmask_b32_e64 v73, v57, 0, vcc
	v_cndmask_b32_e64 v72, v56, 0, vcc
	s_mov_b32 s3, 0x22000
	v_add_co_u32_e64 v76, s[4:5], s3, v82
	s_waitcnt lgkmcnt(1)
; #define LAS __attribute__((address_space(3)))
; DI unsigned pk2(float lo, float hi) { f32x2 v = {lo, hi}; return __builtin_bit_cast(unsigned, __builtin_convertvector(v, bf2_t)); }
; DI f32x16 mfma32(bf16x8 a, bf16x8 b, f32x16 c) { return __builtin_amdgcn_mfma_f32_32x32x16_bf16(a, b, c, 0, 0, 0); }
; DI void attn_sample_unit(LAS unsigned char* lds, const bf16* Q, const float* CK, const float* CV, bf16* AO, int su, int tid, int wave, int lane) {
;     ...
;     for (int c = 0; c < 2; ++c) {
; #pragma unroll
;         for (int hf = 0; hf < 2; ++hf) {
; #pragma unroll
;             for (int i = 0; i < 16; ++i) { u32x2 w; w.x = pk2(v[i][0], v[i][1]); w.y = pk2(v[i][2], v[i][3]); *(LAS u32x2*)(wl + (16 * hf + i) * KV_PITCH + lane * 8) = w; }
;             const int nb = 2 * c + hf + 1;
; #pragma unroll
;             for (int i = 0; i < 16; ++i) v[i] = __builtin_nontemporal_load(nb < 4 ? (const f32x4*)(kb + (size_t)(16 * nb + i) * 1024) : (const f32x4*)(vb + (size_t)i * 1024));
;         }
;         f32x16 a_ = zero16();
; #pragma unroll
;         for (int kk = 0; kk < 16; ++kk) { const bf16x8 a = *(const LAS bf16x8*)(wl + r * KV_PITCH + (16 * kk + 8 * hh) * 2); a_ = mfma32(a, bq[kk], a_); }
;         acc[c] = a_;
	v_mfma_f32_32x32x16_bf16 v[4:19], v[48:51], v[72:75], v[4:19]
	v_addc_co_u32_e64 v77, s[4:5], 0, v83, s[4:5]
	global_load_dwordx4 v[108:111], v[76:77], off offset:-4096
	global_load_dwordx4 v[112:115], v[76:77], off
	v_cndmask_b32_e64 v79, v63, 0, vcc
	v_cndmask_b32_e64 v78, v62, 0, vcc
	v_cndmask_b32_e64 v77, v61, 0, vcc
	v_cndmask_b32_e64 v76, v60, 0, vcc
	ds_read_b128 v[48:51], v122 offset:96
	v_cndmask_b32_e64 v119, v67, 0, vcc
	s_waitcnt lgkmcnt(1)
	v_mfma_f32_32x32x16_bf16 v[4:19], v[52:55], v[76:79], v[4:19]
	v_cndmask_b32_e64 v118, v66, 0, vcc
	v_cndmask_b32_e64 v117, v65, 0, vcc
	v_cndmask_b32_e64 v116, v64, 0, vcc
	ds_read_b128 v[52:55], v122 offset:128
	s_mov_b32 s3, 0x24000
	v_add_co_u32_e64 v56, s[4:5], s3, v82
	s_waitcnt lgkmcnt(1)
	v_mfma_f32_32x32x16_bf16 v[4:19], v[48:51], v[116:119], v[4:19]
	v_addc_co_u32_e64 v57, s[4:5], 0, v83, s[4:5]
	global_load_dwordx4 v[124:127], v[56:57], off offset:-4096
	global_load_dwordx4 v[128:131], v[56:57], off
	v_cndmask_b32_e64 v87, v87, 0, vcc
	v_cndmask_b32_e64 v86, v86, 0, vcc
	v_cndmask_b32_e64 v85, v85, 0, vcc
	v_cndmask_b32_e64 v84, v84, 0, vcc
	ds_read_b128 v[48:51], v122 offset:160
	v_cndmask_b32_e64 v91, v91, 0, vcc
	s_waitcnt lgkmcnt(1)
	v_mfma_f32_32x32x16_bf16 v[4:19], v[52:55], v[84:87], v[4:19]
	v_cndmask_b32_e64 v90, v90, 0, vcc
	v_cndmask_b32_e64 v89, v89, 0, vcc
	v_cndmask_b32_e64 v88, v88, 0, vcc
	ds_read_b128 v[52:55], v122 offset:192
	s_mov_b32 s3, 0x26000
	v_add_co_u32_e64 v56, s[4:5], s3, v82
	s_waitcnt lgkmcnt(1)
	v_mfma_f32_32x32x16_bf16 v[4:19], v[48:51], v[88:91], v[4:19]
	v_addc_co_u32_e64 v57, s[4:5], 0, v83, s[4:5]
	global_load_dwordx4 v[132:135], v[56:57], off offset:-4096
	global_load_dwordx4 v[136:139], v[56:57], off
	v_cndmask_b32_e64 v143, v47, 0, vcc
	v_cndmask_b32_e64 v142, v46, 0, vcc
	v_cndmask_b32_e64 v141, v45, 0, vcc
	v_cndmask_b32_e64 v140, v44, 0, vcc
	ds_read_b128 v[44:47], v122 offset:224
	v_cndmask_b32_e64 v147, v43, 0, vcc
	s_waitcnt lgkmcnt(1)
	v_mfma_f32_32x32x16_bf16 v[4:19], v[52:55], v[140:143], v[4:19]
	v_cndmask_b32_e64 v146, v42, 0, vcc
	v_cndmask_b32_e64 v145, v41, 0, vcc
	v_cndmask_b32_e64 v144, v40, 0, vcc
	ds_read_b128 v[40:43], v122 offset:256
	s_mov_b32 s3, 0x28000
	v_add_co_u32_e64 v48, s[4:5], s3, v82
	s_waitcnt lgkmcnt(1)
	v_mfma_f32_32x32x16_bf16 v[4:19], v[44:47], v[144:147], v[4:19]
	v_addc_co_u32_e64 v49, s[4:5], 0, v83, s[4:5]
	global_load_dwordx4 v[148:151], v[48:49], off offset:-4096
	global_load_dwordx4 v[152:155], v[48:49], off
	v_cndmask_b32_e64 v63, v39, 0, vcc
	v_cndmask_b32_e64 v62, v38, 0, vcc
	v_cndmask_b32_e64 v61, v37, 0, vcc
	v_cndmask_b32_e64 v60, v36, 0, vcc
	ds_read_b128 v[36:39], v122 offset:288
	v_cndmask_b32_e64 v67, v35, 0, vcc
	s_waitcnt lgkmcnt(1)
	v_mfma_f32_32x32x16_bf16 v[4:19], v[40:43], v[60:63], v[4:19]
	v_cndmask_b32_e64 v66, v34, 0, vcc
	v_cndmask_b32_e64 v65, v33, 0, vcc
	v_cndmask_b32_e64 v64, v32, 0, vcc
	ds_read_b128 v[32:35], v122 offset:320
	s_mov_b32 s3, 0x2a000
	v_add_co_u32_e64 v40, s[4:5], s3, v82
	s_waitcnt lgkmcnt(1)
	v_mfma_f32_32x32x16_bf16 v[4:19], v[36:39], v[64:67], v[4:19]
	v_addc_co_u32_e64 v41, s[4:5], 0, v83, s[4:5]
	global_load_dwordx4 v[156:159], v[40:41], off offset:-4096
	global_load_dwordx4 v[160:163], v[40:41], off
	v_cndmask_b32_e64 v59, v31, 0, vcc
	v_cndmask_b32_e64 v58, v30, 0, vcc
	v_cndmask_b32_e64 v57, v29, 0, vcc
	v_cndmask_b32_e64 v56, v28, 0, vcc
	ds_read_b128 v[28:31], v122 offset:352
	v_cndmask_b32_e64 v55, v27, 0, vcc
	s_waitcnt lgkmcnt(1)
	v_mfma_f32_32x32x16_bf16 v[4:19], v[32:35], v[56:59], v[4:19]
	v_cndmask_b32_e64 v54, v26, 0, vcc
	v_cndmask_b32_e64 v53, v25, 0, vcc
	v_cndmask_b32_e64 v52, v24, 0, vcc
	ds_read_b128 v[24:27], v122 offset:384
	s_mov_b32 s3, 0x2c000
	v_add_co_u32_e64 v32, s[4:5], s3, v82
	s_waitcnt lgkmcnt(1)
	v_mfma_f32_32x32x16_bf16 v[4:19], v[28:31], v[52:55], v[4:19]
	v_addc_co_u32_e64 v33, s[4:5], 0, v83, s[4:5]
	global_load_dwordx4 v[28:31], v[32:33], off offset:-4096
	s_nop 0
	global_load_dwordx4 v[32:35], v[32:33], off
	v_cndmask_b32_e64 v51, v23, 0, vcc
	v_cndmask_b32_e64 v50, v22, 0, vcc
	v_cndmask_b32_e64 v49, v21, 0, vcc
	v_cndmask_b32_e64 v48, v20, 0, vcc
	ds_read_b128 v[20:23], v122 offset:416
	s_waitcnt vmcnt(14)
	v_cndmask_b32_e64 v47, v99, 0, vcc
	s_waitcnt lgkmcnt(1)
	v_mfma_f32_32x32x16_bf16 v[4:19], v[24:27], v[48:51], v[4:19]
	v_cndmask_b32_e64 v46, v98, 0, vcc
	v_cndmask_b32_e64 v45, v97, 0, vcc
	v_cndmask_b32_e64 v44, v96, 0, vcc
	ds_read_b128 v[24:27], v122 offset:448
	s_mov_b32 s3, 0x2e000
	v_add_co_u32_e64 v36, s[4:5], s3, v82
	s_waitcnt lgkmcnt(1)
	v_mfma_f32_32x32x16_bf16 v[4:19], v[20:23], v[44:47], v[4:19]
	v_addc_co_u32_e64 v37, s[4:5], 0, v83, s[4:5]
	global_load_dwordx4 v[20:23], v[36:37], off offset:-4096
	global_load_dwordx4 v[96:99], v[36:37], off
	s_waitcnt vmcnt(15)
	v_cndmask_b32_e64 v39, v103, 0, vcc
	v_cndmask_b32_e64 v38, v102, 0, vcc
	v_cndmask_b32_e64 v37, v101, 0, vcc
	v_cndmask_b32_e64 v36, v100, 0, vcc
	ds_read_b128 v[100:103], v122 offset:480
	s_mov_b32 s3, 0x30000
	s_waitcnt lgkmcnt(1)
	v_mfma_f32_32x32x16_bf16 v[4:19], v[24:27], v[36:39], v[4:19]
	v_cvt_pk_bf16_f32 v24, v92, v93
	v_cvt_pk_bf16_f32 v25, v94, v95
	ds_write_b64 v167, v[24:25]
	s_waitcnt vmcnt(13)
	v_cvt_pk_bf16_f32 v24, v108, v109
	v_cvt_pk_bf16_f32 v25, v110, v111
	ds_write_b64 v167, v[24:25] offset:528
	s_waitcnt vmcnt(12)
	v_cvt_pk_bf16_f32 v24, v112, v113
	v_cvt_pk_bf16_f32 v25, v114, v115
	v_add_co_u32_e64 v164, s[4:5], s3, v82
	ds_write_b64 v167, v[24:25] offset:1056
	s_waitcnt vmcnt(11)
; #define LAS __attribute__((address_space(3)))
; DI unsigned pk2(float lo, float hi) { f32x2 v = {lo, hi}; return __builtin_bit_cast(unsigned, __builtin_convertvector(v, bf2_t)); }
; DI f32x16 mfma32(bf16x8 a, bf16x8 b, f32x16 c) { return __builtin_amdgcn_mfma_f32_32x32x16_bf16(a, b, c, 0, 0, 0); }
; DI void attn_sample_unit(LAS unsigned char* lds, const bf16* Q, const float* CK, const float* CV, bf16* AO, int su, int tid, int wave, int lane) {
;     ...
;     for (int c = 0; c < 2; ++c) {
; #pragma unroll
;         for (int hf = 0; hf < 2; ++hf) {
; #pragma unroll
;             for (int i = 0; i < 16; ++i) { u32x2 w; w.x = pk2(v[i][0], v[i][1]); w.y = pk2(v[i][2], v[i][3]); *(LAS u32x2*)(wl + (16 * hf + i) * KV_PITCH + lane * 8) = w; }
;             const int nb = 2 * c + hf + 1;
; #pragma unroll
;             for (int i = 0; i < 16; ++i) v[i] = __builtin_nontemporal_load(nb < 4 ? (const f32x4*)(kb + (size_t)(16 * nb + i) * 1024) : (const f32x4*)(vb + (size_t)i * 1024));
;         }
;         f32x16 a_ = zero16();
; #pragma unroll
;         for (int kk = 0; kk < 16; ++kk) { const bf16x8 a = *(const LAS bf16x8*)(wl + r * KV_PITCH + (16 * kk + 8 * hh) * 2); a_ = mfma32(a, bq[kk], a_); }
;         acc[c] = a_;
	v_cvt_pk_bf16_f32 v24, v124, v125
	v_cvt_pk_bf16_f32 v25, v126, v127
	s_mov_b32 s3, 0x32000
	v_addc_co_u32_e64 v165, s[4:5], 0, v83, s[4:5]
	v_cndmask_b32_e64 v43, v107, 0, vcc
	v_cndmask_b32_e64 v42, v106, 0, vcc
	v_cndmask_b32_e64 v41, v105, 0, vcc
	v_cndmask_b32_e64 v40, v104, 0, vcc
	ds_write_b64 v167, v[24:25] offset:1584
	v_add_co_u32_e32 v104, vcc, s3, v82
	global_load_dwordx4 v[24:27], v[164:165], off offset:-4096
	global_load_dwordx4 v[92:95], v[164:165], off
	v_addc_co_u32_e32 v105, vcc, 0, v83, vcc
	s_mov_b32 s3, 0x34000
	v_add_co_u32_e32 v112, vcc, s3, v82
	s_waitcnt lgkmcnt(4)
	v_mfma_f32_32x32x16_bf16 v[4:19], v[100:103], v[40:43], v[4:19]
	global_load_dwordx4 v[100:103], v[104:105], off offset:-4096
	s_nop 0
	global_load_dwordx4 v[104:107], v[104:105], off
	v_addc_co_u32_e32 v113, vcc, 0, v83, vcc
	s_mov_b32 s3, 0x36000
	s_waitcnt vmcnt(14)
	v_cvt_pk_bf16_f32 v216, v128, v129
	v_add_co_u32_e32 v128, vcc, s3, v82
	global_load_dwordx4 v[108:111], v[112:113], off offset:-4096
	s_nop 0
	global_load_dwordx4 v[112:115], v[112:113], off
	v_addc_co_u32_e32 v129, vcc, 0, v83, vcc
	s_mov_b32 s3, 0x38000
	v_add_co_u32_e32 v164, vcc, s3, v82
	v_cvt_pk_bf16_f32 v217, v130, v131
	global_load_dwordx4 v[124:127], v[128:129], off offset:-4096
	s_nop 0
	global_load_dwordx4 v[128:131], v[128:129], off
	v_addc_co_u32_e32 v165, vcc, 0, v83, vcc
	s_mov_b32 s3, 0x3a000
	global_load_dwordx4 v[170:173], v[164:165], off offset:-4096
	global_load_dwordx4 v[174:177], v[164:165], off
	v_add_co_u32_e32 v164, vcc, s3, v82
	s_mov_b32 s3, 0x3c000
	s_nop 0
	v_addc_co_u32_e32 v165, vcc, 0, v83, vcc
	global_load_dwordx4 v[178:181], v[164:165], off offset:-4096
	global_load_dwordx4 v[182:185], v[164:165], off
	v_add_co_u32_e32 v164, vcc, s3, v82
	s_mov_b32 s3, 0x3e000
	s_nop 0
	v_addc_co_u32_e32 v165, vcc, 0, v83, vcc
	global_load_dwordx4 v[186:189], v[164:165], off offset:-4096
	global_load_dwordx4 v[190:193], v[164:165], off
	v_add_co_u32_e32 v164, vcc, s3, v82
	s_mov_b32 s3, 0x3f000
	s_nop 0
	v_addc_co_u32_e32 v165, vcc, 0, v83, vcc
	v_add_co_u32_e32 v82, vcc, s3, v82
	global_load_dwordx4 v[194:197], v[164:165], off offset:-4096
	global_load_dwordx4 v[198:201], v[164:165], off
	v_addc_co_u32_e32 v83, vcc, 0, v83, vcc
	global_load_dwordx4 v[212:215], v[82:83], off
	s_waitcnt vmcnt(18)
	v_cvt_pk_bf16_f32 v20, v20, v21
	v_cvt_pk_bf16_f32 v21, v22, v23
	ds_write_b64 v167, v[20:21] offset:6864
	s_waitcnt vmcnt(17)
	v_cvt_pk_bf16_f32 v20, v96, v97
	v_cvt_pk_bf16_f32 v21, v98, v99
	ds_write_b64 v167, v[20:21] offset:7392
	v_cvt_pk_bf16_f32 v82, v132, v133
	v_cvt_pk_bf16_f32 v83, v134, v135
	ds_write_b64 v167, v[82:83] offset:2640
	v_cvt_pk_bf16_f32 v82, v136, v137
	v_cvt_pk_bf16_f32 v83, v138, v139
	ds_write_b64 v167, v[82:83] offset:3168
	v_cvt_pk_bf16_f32 v82, v148, v149
	v_cvt_pk_bf16_f32 v83, v150, v151
	ds_write_b64 v167, v[82:83] offset:3696
	v_cvt_pk_bf16_f32 v82, v152, v153
	v_cvt_pk_bf16_f32 v83, v154, v155
	ds_write_b64 v167, v[82:83] offset:4224
	v_cvt_pk_bf16_f32 v82, v156, v157
	v_cvt_pk_bf16_f32 v83, v158, v159
	v_cvt_pk_bf16_f32 v28, v28, v29
	v_cvt_pk_bf16_f32 v29, v30, v31
	ds_write_b64 v167, v[82:83] offset:4752
	v_cvt_pk_bf16_f32 v82, v160, v161
	v_cvt_pk_bf16_f32 v83, v162, v163
	ds_write_b64 v167, v[28:29] offset:5808
	v_cvt_pk_bf16_f32 v28, v32, v33
	v_cvt_pk_bf16_f32 v29, v34, v35
	ds_write_b64 v167, v[216:217] offset:2112
	ds_write_b64 v167, v[82:83] offset:5280
	s_waitcnt vmcnt(16)
	v_cvt_pk_bf16_f32 v20, v24, v25
	v_cvt_pk_bf16_f32 v21, v26, v27
	ds_write_b64 v167, v[20:21] offset:7920
	s_waitcnt vmcnt(15)
	v_cvt_pk_bf16_f32 v20, v92, v93
	v_cvt_pk_bf16_f32 v21, v94, v95
	ds_write_b64 v167, v[20:21] offset:8448
	ds_write_b64 v167, v[28:29] offset:6336
	s_waitcnt vmcnt(14)
	v_cvt_pk_bf16_f32 v20, v100, v101
	v_cvt_pk_bf16_f32 v21, v102, v103
	ds_write_b64 v167, v[20:21] offset:8976
	s_waitcnt vmcnt(13)
	v_cvt_pk_bf16_f32 v20, v104, v105
	v_cvt_pk_bf16_f32 v21, v106, v107
	ds_write_b64 v167, v[20:21] offset:9504
	s_mov_b32 s3, 0xf000
	s_waitcnt vmcnt(12)
	v_cvt_pk_bf16_f32 v20, v108, v109
	v_cvt_pk_bf16_f32 v21, v110, v111
	ds_write_b64 v167, v[20:21] offset:10032
	s_waitcnt vmcnt(11)
	v_cvt_pk_bf16_f32 v20, v112, v113
	v_cvt_pk_bf16_f32 v21, v114, v115
	ds_write_b64 v167, v[20:21] offset:10560
	s_waitcnt vmcnt(10)
	v_cvt_pk_bf16_f32 v20, v124, v125
	v_cvt_pk_bf16_f32 v21, v126, v127
	ds_write_b64 v167, v[20:21] offset:11088
	s_waitcnt vmcnt(9)
	v_cvt_pk_bf16_f32 v20, v128, v129
	v_cvt_pk_bf16_f32 v21, v130, v131
	ds_write_b64 v167, v[20:21] offset:11616
	s_waitcnt vmcnt(8)
	v_cvt_pk_bf16_f32 v20, v170, v171
	v_cvt_pk_bf16_f32 v21, v172, v173
	ds_write_b64 v167, v[20:21] offset:12144
	s_waitcnt vmcnt(7)
	v_cvt_pk_bf16_f32 v20, v174, v175
	v_cvt_pk_bf16_f32 v21, v176, v177
	ds_write_b64 v167, v[20:21] offset:12672
	s_waitcnt vmcnt(6)
	v_cvt_pk_bf16_f32 v20, v178, v179
	v_cvt_pk_bf16_f32 v21, v180, v181
	ds_write_b64 v167, v[20:21] offset:13200
	s_waitcnt vmcnt(5)
	v_cvt_pk_bf16_f32 v20, v182, v183
	v_cvt_pk_bf16_f32 v21, v184, v185
	ds_write_b64 v167, v[20:21] offset:13728
	s_waitcnt vmcnt(4)
	v_cvt_pk_bf16_f32 v20, v186, v187
	v_cvt_pk_bf16_f32 v21, v188, v189
	ds_write_b64 v167, v[20:21] offset:14256
	s_waitcnt vmcnt(3)
	v_cvt_pk_bf16_f32 v20, v190, v191
	v_cvt_pk_bf16_f32 v21, v192, v193
	ds_write_b64 v167, v[20:21] offset:14784
	s_waitcnt vmcnt(2)
	v_cvt_pk_bf16_f32 v20, v194, v195
	v_cvt_pk_bf16_f32 v21, v196, v197
	ds_write_b64 v167, v[20:21] offset:15312
	s_waitcnt vmcnt(1)
	v_cvt_pk_bf16_f32 v20, v198, v199
	v_cvt_pk_bf16_f32 v21, v200, v201
	ds_write_b64 v167, v[20:21] offset:15840
	s_waitcnt vmcnt(0)
; #define LAS __attribute__((address_space(3)))
; DI float xmax32(float v) { const unsigned u = __float_as_uint(v); const u32x2p r = __builtin_amdgcn_permlane32_swap(u, u, false, false); return fmaxf(__uint_as_float(r[0]), __uint_as_float(r[1])); }
; DI f32x16 mfma32(bf16x8 a, bf16x8 b, f32x16 c) { return __builtin_amdgcn_mfma_f32_32x32x16_bf16(a, b, c, 0, 0, 0); }
; DI void attn_sample_unit(LAS unsigned char* lds, const bf16* Q, const float* CK, const float* CV, bf16* AO, int su, int tid, int wave, int lane) {
;     ...
;             for (int i = 0; i < 16; ++i) v[i] = __builtin_nontemporal_load(nb < 4 ? (const f32x4*)(kb + (size_t)(16 * nb + i) * 1024) : (const f32x4*)(vb + (size_t)i * 1024));
;         }
;         f32x16 a_ = zero16();
; #pragma unroll
;         for (int kk = 0; kk < 16; ++kk) { const bf16x8 a = *(const LAS bf16x8*)(wl + r * KV_PITCH + (16 * kk + 8 * hh) * 2); a_ = mfma32(a, bq[kk], a_); }
;         acc[c] = a_;
;     }
;     float mx = -3.0e38f;
; #pragma unroll
;     for (int c = 0; c < 2; ++c)
; #pragma unroll
;         for (int i = 0; i < 16; ++i) mx = fmaxf(mx, acc[c][i]);
;     mx = xmax32(mx);
	v_cvt_pk_bf16_f32 v20, v212, v213
	v_cvt_pk_bf16_f32 v21, v214, v215
	ds_write_b64 v167, v[20:21] offset:16368
	ds_read_b128 v[20:23], v122
	s_waitcnt lgkmcnt(0)
	v_mfma_f32_32x32x16_bf16 v[20:35], v[20:23], v[68:71], 0
	ds_read_b128 v[68:71], v122 offset:32
	s_waitcnt lgkmcnt(0)
	v_mfma_f32_32x32x16_bf16 v[20:35], v[68:71], v[72:75], v[20:35]
	ds_read_b128 v[68:71], v122 offset:64
	s_waitcnt lgkmcnt(0)
	v_mfma_f32_32x32x16_bf16 v[20:35], v[68:71], v[76:79], v[20:35]
	ds_read_b128 v[68:71], v122 offset:96
	s_waitcnt lgkmcnt(0)
	v_mfma_f32_32x32x16_bf16 v[20:35], v[68:71], v[116:119], v[20:35]
	ds_read_b128 v[68:71], v122 offset:128
	s_waitcnt lgkmcnt(0)
	v_mfma_f32_32x32x16_bf16 v[20:35], v[68:71], v[84:87], v[20:35]
	ds_read_b128 v[68:71], v122 offset:160
	s_waitcnt lgkmcnt(0)
	v_mfma_f32_32x32x16_bf16 v[20:35], v[68:71], v[88:91], v[20:35]
	ds_read_b128 v[68:71], v122 offset:192
	s_waitcnt lgkmcnt(0)
	v_mfma_f32_32x32x16_bf16 v[20:35], v[68:71], v[140:143], v[20:35]
	ds_read_b128 v[72:75], v122 offset:224
	ds_read_b128 v[68:71], v122 offset:256
	ds_read_b128 v[76:79], v122 offset:288
	v_lshl_add_u64 v[140:141], s[20:21], 0, v[80:81]
	s_waitcnt lgkmcnt(2)
	v_mfma_f32_32x32x16_bf16 v[20:35], v[72:75], v[144:147], v[20:35]
	global_load_dwordx4 v[72:75], v80, s[20:21] nt
	v_add_co_u32_e32 v80, vcc, s33, v140
	s_nop 1
	v_addc_co_u32_e32 v81, vcc, 0, v141, vcc
	global_load_dwordx4 v[128:131], v[80:81], off offset:-4096 nt
	global_load_dwordx4 v[116:119], v[80:81], off nt
	s_waitcnt lgkmcnt(1)
	v_mfma_f32_32x32x16_bf16 v[20:35], v[68:71], v[60:63], v[20:35]
	ds_read_b128 v[60:63], v122 offset:320
	v_add_co_u32_e32 v68, vcc, s44, v140
	s_nop 1
	v_addc_co_u32_e32 v69, vcc, 0, v141, vcc
	global_load_dwordx4 v[112:115], v[68:69], off offset:-4096 nt
	global_load_dwordx4 v[108:111], v[68:69], off nt
	s_waitcnt lgkmcnt(1)
	v_mfma_f32_32x32x16_bf16 v[20:35], v[76:79], v[64:67], v[20:35]
	ds_read_b128 v[64:67], v122 offset:352
	v_add_co_u32_e32 v68, vcc, s27, v140
	s_nop 1
	v_addc_co_u32_e32 v69, vcc, 0, v141, vcc
	global_load_dwordx4 v[104:107], v[68:69], off offset:-4096 nt
	global_load_dwordx4 v[100:103], v[68:69], off nt
	s_waitcnt lgkmcnt(1)
	v_mfma_f32_32x32x16_bf16 v[20:35], v[60:63], v[56:59], v[20:35]
	ds_read_b128 v[56:59], v122 offset:384
	v_add_co_u32_e32 v60, vcc, s30, v140
	s_nop 1
	v_addc_co_u32_e32 v61, vcc, 0, v141, vcc
	global_load_dwordx4 v[96:99], v[60:61], off offset:-4096 nt
	global_load_dwordx4 v[92:95], v[60:61], off nt
	s_waitcnt lgkmcnt(1)
	v_mfma_f32_32x32x16_bf16 v[20:35], v[64:67], v[52:55], v[20:35]
	ds_read_b128 v[52:55], v122 offset:416
	v_add_co_u32_e32 v60, vcc, s31, v140
	s_nop 1
	v_addc_co_u32_e32 v61, vcc, 0, v141, vcc
	global_load_dwordx4 v[88:91], v[60:61], off offset:-4096 nt
	global_load_dwordx4 v[84:87], v[60:61], off nt
	s_waitcnt lgkmcnt(1)
	v_mfma_f32_32x32x16_bf16 v[20:35], v[56:59], v[48:51], v[20:35]
	ds_read_b128 v[48:51], v122 offset:448
	v_add_co_u32_e32 v56, vcc, s36, v140
	s_nop 1
	v_addc_co_u32_e32 v57, vcc, 0, v141, vcc
	global_load_dwordx4 v[80:83], v[56:57], off offset:-4096 nt
	global_load_dwordx4 v[76:79], v[56:57], off nt
	s_waitcnt lgkmcnt(1)
	v_mfma_f32_32x32x16_bf16 v[20:35], v[52:55], v[44:47], v[20:35]
	v_add_co_u32_e32 v52, vcc, s37, v140
	ds_read_b128 v[44:47], v122 offset:480
	s_nop 0
	v_addc_co_u32_e32 v53, vcc, 0, v141, vcc
	global_load_dwordx4 v[68:71], v[52:53], off offset:-4096 nt
	global_load_dwordx4 v[64:67], v[52:53], off nt
	s_waitcnt lgkmcnt(1)
	v_mfma_f32_32x32x16_bf16 v[20:35], v[48:51], v[36:39], v[20:35]
	v_add_co_u32_e32 v36, vcc, s3, v140
	s_mov_b32 s3, 0xff61b1e6
	s_nop 0
	v_addc_co_u32_e32 v37, vcc, 0, v141, vcc
	global_load_dwordx4 v[52:55], v[36:37], off nt
	v_max3_f32 v36, v4, s3, v5
	s_waitcnt lgkmcnt(0)
; #define LAS __attribute__((address_space(3)))
; DI float xsum32(float v) { const unsigned u = __float_as_uint(v); const u32x2p r = __builtin_amdgcn_permlane32_swap(u, u, false, false); return __uint_as_float(r[0]) + __uint_as_float(r[1]); }
; DI float xmax32(float v) { const unsigned u = __float_as_uint(v); const u32x2p r = __builtin_amdgcn_permlane32_swap(u, u, false, false); return fmaxf(__uint_as_float(r[0]), __uint_as_float(r[1])); }
; DI int crow(int i, int hh) { return (i & 3) + 8 * (i >> 2) + 4 * hh; }
; DI void attn_sample_unit(LAS unsigned char* lds, const bf16* Q, const float* CK, const float* CV, bf16* AO, int su, int tid, int wave, int lane) {
;     ...
;     float mx = -3.0e38f;
; #pragma unroll
;     for (int c = 0; c < 2; ++c)
; #pragma unroll
;         for (int i = 0; i < 16; ++i) mx = fmaxf(mx, acc[c][i]);
;     mx = xmax32(mx);
;     float sum = 0.f;
; #pragma unroll
;     for (int c = 0; c < 2; ++c)
; #pragma unroll
;         for (int i = 0; i < 16; ++i) { const float p = __builtin_amdgcn_exp2f((acc[c][i] - mx) * LOG2E); acc[c][i] = p; sum += p; }
;     sum = xsum32(sum);
;     LAS float* Pbuf = (LAS float*)wl;
;     if (r < 8) {
; #pragma unroll
;         for (int c = 0; c < 2; ++c)
; #pragma unroll
;             for (int i = 0; i < 16; ++i) Pbuf[(32 * c + crow(i, hh)) * 8 + r] = acc[c][i];
;     }
	v_mfma_f32_32x32x16_bf16 v[20:35], v[44:47], v[40:43], v[20:35]
	v_max3_f32 v36, v36, v6, v7
	v_max3_f32 v36, v36, v8, v9
	v_max3_f32 v36, v36, v10, v11
	v_max3_f32 v36, v36, v12, v13
	v_max3_f32 v36, v36, v14, v15
	v_max3_f32 v36, v36, v16, v17
	v_max3_f32 v36, v36, v18, v19
	s_nop 4
	v_max3_f32 v36, v36, v20, v21
	v_max3_f32 v36, v36, v22, v23
	v_max3_f32 v36, v36, v24, v25
	v_max3_f32 v36, v36, v26, v27
	v_max3_f32 v36, v36, v28, v29
	v_max3_f32 v36, v36, v30, v31
	v_max3_f32 v36, v36, v32, v33
	v_max3_f32 v36, v36, v34, v35
	v_mov_b32_e32 v37, v36
	s_nop 1
	v_permlane32_swap_b32_e32 v36, v37
	v_max_f32_e32 v37, v37, v37
	v_max_f32_e32 v36, v36, v36
	v_max_f32_e32 v148, v36, v37
	v_sub_f32_e32 v4, v4, v148
	v_mul_f32_e32 v4, 0x3fb8aa3b, v4
	v_sub_f32_e32 v5, v5, v148
	v_exp_f32_e32 v4, v4
	v_mul_f32_e32 v5, 0x3fb8aa3b, v5
	v_sub_f32_e32 v6, v6, v148
	v_exp_f32_e32 v5, v5
	v_mul_f32_e32 v6, 0x3fb8aa3b, v6
	v_sub_f32_e32 v7, v7, v148
	v_exp_f32_e32 v6, v6
	v_mul_f32_e32 v7, 0x3fb8aa3b, v7
	v_sub_f32_e32 v8, v8, v148
	v_exp_f32_e32 v7, v7
	v_mul_f32_e32 v8, 0x3fb8aa3b, v8
	v_sub_f32_e32 v9, v9, v148
	v_add_f32_e32 v36, 0, v4
	v_exp_f32_e32 v8, v8
	v_mul_f32_e32 v9, 0x3fb8aa3b, v9
	v_sub_f32_e32 v10, v10, v148
	v_add_f32_e32 v36, v5, v36
	v_exp_f32_e32 v9, v9
	v_mul_f32_e32 v10, 0x3fb8aa3b, v10
	v_sub_f32_e32 v11, v11, v148
	v_add_f32_e32 v36, v6, v36
	v_exp_f32_e32 v10, v10
	v_mul_f32_e32 v11, 0x3fb8aa3b, v11
	v_sub_f32_e32 v12, v12, v148
	v_add_f32_e32 v36, v7, v36
	v_exp_f32_e32 v11, v11
	v_mul_f32_e32 v12, 0x3fb8aa3b, v12
	v_sub_f32_e32 v13, v13, v148
	v_add_f32_e32 v36, v8, v36
	v_exp_f32_e32 v12, v12
	v_mul_f32_e32 v13, 0x3fb8aa3b, v13
	v_sub_f32_e32 v14, v14, v148
	v_add_f32_e32 v36, v9, v36
	v_exp_f32_e32 v13, v13
	v_mul_f32_e32 v14, 0x3fb8aa3b, v14
	v_sub_f32_e32 v15, v15, v148
	v_add_f32_e32 v36, v10, v36
	v_exp_f32_e32 v14, v14
	v_mul_f32_e32 v15, 0x3fb8aa3b, v15
	v_sub_f32_e32 v16, v16, v148
	v_add_f32_e32 v36, v11, v36
	v_exp_f32_e32 v15, v15
	v_mul_f32_e32 v16, 0x3fb8aa3b, v16
	v_sub_f32_e32 v17, v17, v148
	v_add_f32_e32 v36, v12, v36
	v_exp_f32_e32 v16, v16
	v_mul_f32_e32 v17, 0x3fb8aa3b, v17
	v_sub_f32_e32 v18, v18, v148
	v_add_f32_e32 v36, v13, v36
	v_exp_f32_e32 v17, v17
	v_mul_f32_e32 v18, 0x3fb8aa3b, v18
	v_sub_f32_e32 v19, v19, v148
	v_add_f32_e32 v36, v14, v36
	v_exp_f32_e32 v18, v18
	v_mul_f32_e32 v19, 0x3fb8aa3b, v19
	v_sub_f32_e32 v20, v20, v148
	v_add_f32_e32 v36, v15, v36
	v_exp_f32_e32 v19, v19
	v_mul_f32_e32 v20, 0x3fb8aa3b, v20
	v_sub_f32_e32 v21, v21, v148
	v_add_f32_e32 v36, v16, v36
	v_exp_f32_e32 v20, v20
	v_mul_f32_e32 v21, 0x3fb8aa3b, v21
	v_sub_f32_e32 v22, v22, v148
	v_add_f32_e32 v36, v17, v36
	v_exp_f32_e32 v21, v21
	v_mul_f32_e32 v22, 0x3fb8aa3b, v22
	v_sub_f32_e32 v23, v23, v148
	v_add_f32_e32 v36, v18, v36
	v_exp_f32_e32 v22, v22
	v_mul_f32_e32 v23, 0x3fb8aa3b, v23
	v_sub_f32_e32 v24, v24, v148
	v_add_f32_e32 v36, v19, v36
	v_exp_f32_e32 v23, v23
	v_mul_f32_e32 v24, 0x3fb8aa3b, v24
	v_sub_f32_e32 v25, v25, v148
	v_add_f32_e32 v36, v20, v36
	v_exp_f32_e32 v24, v24
	v_mul_f32_e32 v25, 0x3fb8aa3b, v25
	v_sub_f32_e32 v26, v26, v148
	v_add_f32_e32 v36, v21, v36
	v_exp_f32_e32 v25, v25
	v_mul_f32_e32 v26, 0x3fb8aa3b, v26
	v_sub_f32_e32 v27, v27, v148
	v_add_f32_e32 v36, v22, v36
	v_exp_f32_e32 v26, v26
	v_mul_f32_e32 v27, 0x3fb8aa3b, v27
	v_sub_f32_e32 v28, v28, v148
	v_add_f32_e32 v36, v23, v36
	v_exp_f32_e32 v27, v27
	v_mul_f32_e32 v28, 0x3fb8aa3b, v28
	v_sub_f32_e32 v29, v29, v148
	v_add_f32_e32 v36, v24, v36
	v_exp_f32_e32 v28, v28
	v_mul_f32_e32 v29, 0x3fb8aa3b, v29
	v_sub_f32_e32 v30, v30, v148
	v_add_f32_e32 v36, v25, v36
	v_exp_f32_e32 v29, v29
	v_mul_f32_e32 v30, 0x3fb8aa3b, v30
	v_sub_f32_e32 v31, v31, v148
	v_add_f32_e32 v36, v26, v36
	v_exp_f32_e32 v30, v30
	v_mul_f32_e32 v31, 0x3fb8aa3b, v31
	v_sub_f32_e32 v32, v32, v148
	v_add_f32_e32 v36, v27, v36
	v_exp_f32_e32 v31, v31
	v_mul_f32_e32 v32, 0x3fb8aa3b, v32
	v_sub_f32_e32 v33, v33, v148
	v_add_f32_e32 v36, v28, v36
	v_exp_f32_e32 v32, v32
	v_mul_f32_e32 v33, 0x3fb8aa3b, v33
	v_sub_f32_e32 v34, v34, v148
	v_add_f32_e32 v36, v29, v36
	v_exp_f32_e32 v33, v33
	v_mul_f32_e32 v34, 0x3fb8aa3b, v34
	v_sub_f32_e32 v35, v35, v148
	v_add_f32_e32 v36, v30, v36
	v_exp_f32_e32 v34, v34
	v_mul_f32_e32 v35, 0x3fb8aa3b, v35
	v_add_f32_e32 v36, v31, v36
	v_exp_f32_e32 v35, v35
	v_add_f32_e32 v36, v32, v36
	v_add_f32_e32 v36, v33, v36
	v_add_f32_e32 v36, v34, v36
	v_add_f32_e32 v149, v35, v36
	v_mov_b32_e32 v170, v149
	s_nop 1
	v_permlane32_swap_b32_e32 v149, v170
	v_cmp_gt_u32_e32 vcc, 8, v120
	s_and_saveexec_b64 s[4:5], vcc
	s_cbranch_execz .LBB0_1182
	v_lshlrev_b32_e32 v36, 7, v121
	v_lshlrev_b32_e32 v37, 2, v120
	v_add3_u32 v36, s28, v36, v37
	ds_write2_b32 v36, v4, v5 offset1:8
	ds_write2_b32 v36, v6, v7 offset0:16 offset1:24
	ds_write2_b32 v36, v8, v9 offset0:64 offset1:72
	ds_write2_b32 v36, v10, v11 offset0:80 offset1:88
	ds_write2_b32 v36, v12, v13 offset0:128 offset1:136
	ds_write2_b32 v36, v14, v15 offset0:144 offset1:152
	ds_write2_b32 v36, v16, v17 offset0:192 offset1:200
	ds_write2_b32 v36, v18, v19 offset0:208 offset1:216
	v_add_u32_e32 v4, 0x400, v36
	ds_write2_b32 v4, v20, v21 offset1:8
	ds_write2_b32 v4, v22, v23 offset0:16 offset1:24
	ds_write2_b32 v4, v24, v25 offset0:64 offset1:72
	ds_write2_b32 v4, v26, v27 offset0:80 offset1:88
	ds_write2_b32 v4, v28, v29 offset0:128 offset1:136
	ds_write2_b32 v4, v30, v31 offset0:144 offset1:152
	ds_write2_b32 v4, v32, v33 offset0:192 offset1:200
	ds_write2_b32 v4, v34, v35 offset0:208 offset1:216

; __device__ __forceinline__ void grp_barrier(const XcdBarrier& b, unsigned gsz) {
;     asm volatile("s_waitcnt vmcnt(0)" ::: "memory");
;     __syncthreads();
.LBB0_1195:
	s_mov_b64 s[4:5], s[48:49]
	s_mov_b32 s10, s2
	s_getreg_b32 s3, hwreg(HW_REG_XCC_ID, 0, 4)
	s_waitcnt vmcnt(0)
	v_readfirstlane_b32 s0, v0
	s_nop 3
	s_lshr_b32 s0, s0, 6
	s_cmp_eq_u32 s0, 1
	s_cbranch_scc0 .Lgb_noinv8
	buffer_inv sc1

; __device__ __forceinline__ unsigned xb_ld(unsigned* p)              { return __hip_atomic_load(p, __ATOMIC_RELAXED, __HIP_MEMORY_SCOPE_AGENT); }
; __device__ __forceinline__ unsigned xb_add(unsigned* p, unsigned v) { return __hip_atomic_fetch_add(p, v, __ATOMIC_RELAXED, __HIP_MEMORY_SCOPE_AGENT); }
; #define XB_SPIN(cond, bar) do { unsigned _sp = 0; while (cond) { __builtin_amdgcn_s_sleep(1); \
;     if ((++_sp & 255u) == 0u) { if (xb_ld(&(bar)[XB_TMO])) break; if (_sp > XB_SPIN_CAP) { atomicAdd(&(bar)[XB_TMO], 1u); break; } } } } while (0)
; __device__ __forceinline__ void grp_barrier(const XcdBarrier& b, unsigned gsz) {
;     ...
;         const unsigned old = xb_add(&bar[XB_XSUB(b.x)], 1u);
;         const bool early = (nx == 1u);
;         if (early) __builtin_amdgcn_fence(__ATOMIC_ACQUIRE, "agent");
;         const unsigned gen = old / nloc;
;         if (old + 1u == (gen + 1u) * nloc) {
;             if (nx > 1u) __builtin_amdgcn_fence(__ATOMIC_RELEASE, "agent");
;             if (!early) asm volatile("s_waitcnt vmcnt(0)" ::: "memory");
;             if (!early) {
;             const unsigned og = xb_add(&bar[XB_TOP], 1u);
;             const unsigned tg = og / nx;
;             if (og + 1u == (tg + 1u) * nx) xb_add(&bar[XB_TOPGEN], 1u);
;             else XB_SPIN(xb_ld(&bar[XB_TOPGEN]) == tg, bar);
;             }
;             if (!early) __builtin_amdgcn_fence(__ATOMIC_ACQUIRE, "agent");
;             xb_add(&bar[XB_XGEN(b.x)], 1u);
;             asm volatile("s_waitcnt vmcnt(0)" ::: "memory");
;         } else {
;             XB_SPIN(xb_ld(&bar[XB_XGEN(b.x)]) == gen, bar);
.LBB0_1213:
	s_or_b64 exec, exec, s[14:15]
	s_waitcnt lgkmcnt(0)
	v_cmp_eq_u32_e32 vcc, 1, v4
	s_cbranch_vccz .Lgb_slow8
	global_load_dword v7, v202, s[12:13] offset:1024 sc1
	s_mov_b32 s3, 0
	s_waitcnt vmcnt(1)
	v_and_b32_e32 v3, 31, v6
	v_and_b32_e32 v6, 0xffffffe0, v6
	v_cmp_eq_u32_e32 vcc, 31, v3
	v_add_u32_e32 v6, 32, v6
	s_cbranch_vccz .Lgb_poll8
	global_atomic_add v203, v205, s[12:13] offset:1024
	s_branch .Lgb_done8

; __device__ __forceinline__ void grp_barrier(const XcdBarrier& b, unsigned gsz) {
;     ...
;     __syncthreads();
; __global__ void __launch_bounds__(NTHREADS, 2) hybrid_fwd(Args Aval) {
;     ...
;         {   PHASE_BEGIN
;             const pg8::bf16_t* W = (const pg8::bf16_t*)(ws + WS_WO) + (size_t)l * DM * DM;
;             pg8::Gemm g{(const pg8::bf16_t*)(ws + WS_A2), W, MP, DM, DM}; pg8::GroupOrder S{8, 4, grp, rank};
;             pg8::BigEpi<pg8::XupdR8> E{{(pg8::bf16_t*)(ws + WS_XB), (float*)(ws + WS_SSQ), 1.f}};
;             pg8::gemm_phase<pg8::BigEpi<pg8::XupdR8>, pg8::GroupOrder, true, true>(lds, g, S, E, tid);
.LBB0_1255:
	s_or_b64 exec, exec, s[0:1]
	s_mov_b64 s[0:1], s[48:49]
	s_mov_b32 s3, s2
	v_mov_b32_e32 v3, v0
	s_waitcnt vmcnt(0)
	s_barrier
	s_load_dwordx2 s[0:1], s[0:1], 0x110
	s_and_b32 s27, s3, 7
	s_ashr_i32 s34, s3, 3
	s_cmp_lt_i32 s34, 32
	s_cselect_b64 s[4:5], -1, 0
	s_cmp_gt_i32 s34, 31
	v_readfirstlane_b32 s16, v3
	s_cbranch_scc1 .LBB0_1257
	s_ashr_i32 s11, s34, 31
	s_lshr_b32 s11, s11, 29
	s_add_i32 s11, s34, s11
	s_ashr_i32 s28, s11, 3
	s_and_b32 s11, s11, -8
	s_lshl_b32 s10, s27, 3
	s_sub_i32 s11, s34, s11
	s_add_i32 s30, s10, s11

; __device__ __forceinline__ void grp_barrier(const XcdBarrier& b, unsigned gsz) {
;     asm volatile("s_waitcnt vmcnt(0)" ::: "memory");
;     __syncthreads();
.LBB0_1309:
	s_or_b64 exec, exec, s[4:5]
	s_mov_b64 s[4:5], s[48:49]
	s_mov_b32 s8, s2
	s_getreg_b32 s3, hwreg(HW_REG_XCC_ID, 0, 4)
	s_waitcnt vmcnt(0)
	v_readfirstlane_b32 s0, v0
	s_nop 3
	s_lshr_b32 s0, s0, 6
	s_cmp_eq_u32 s0, 1
	s_cbranch_scc0 .Lgb_noinv9
	buffer_inv sc1

; __device__ __forceinline__ unsigned xb_ld(unsigned* p)              { return __hip_atomic_load(p, __ATOMIC_RELAXED, __HIP_MEMORY_SCOPE_AGENT); }
; __device__ __forceinline__ unsigned xb_add(unsigned* p, unsigned v) { return __hip_atomic_fetch_add(p, v, __ATOMIC_RELAXED, __HIP_MEMORY_SCOPE_AGENT); }
; #define XB_SPIN(cond, bar) do { unsigned _sp = 0; while (cond) { __builtin_amdgcn_s_sleep(1); \
;     if ((++_sp & 255u) == 0u) { if (xb_ld(&(bar)[XB_TMO])) break; if (_sp > XB_SPIN_CAP) { atomicAdd(&(bar)[XB_TMO], 1u); break; } } } } while (0)
; __device__ __forceinline__ void grp_barrier(const XcdBarrier& b, unsigned gsz) {
;     ...
;         const unsigned old = xb_add(&bar[XB_XSUB(b.x)], 1u);
;         const bool early = (nx == 1u);
;         if (early) __builtin_amdgcn_fence(__ATOMIC_ACQUIRE, "agent");
;         const unsigned gen = old / nloc;
;         if (old + 1u == (gen + 1u) * nloc) {
;             if (nx > 1u) __builtin_amdgcn_fence(__ATOMIC_RELEASE, "agent");
;             if (!early) asm volatile("s_waitcnt vmcnt(0)" ::: "memory");
;             if (!early) {
;             const unsigned og = xb_add(&bar[XB_TOP], 1u);
;             const unsigned tg = og / nx;
;             if (og + 1u == (tg + 1u) * nx) xb_add(&bar[XB_TOPGEN], 1u);
;             else XB_SPIN(xb_ld(&bar[XB_TOPGEN]) == tg, bar);
;             }
;             if (!early) __builtin_amdgcn_fence(__ATOMIC_ACQUIRE, "agent");
;             xb_add(&bar[XB_XGEN(b.x)], 1u);
;             asm volatile("s_waitcnt vmcnt(0)" ::: "memory");
;         } else {
;             XB_SPIN(xb_ld(&bar[XB_XGEN(b.x)]) == gen, bar);
.LBB0_1327:
	s_or_b64 exec, exec, s[12:13]
	s_waitcnt lgkmcnt(0)
	v_cmp_eq_u32_e32 vcc, 1, v4
	s_cbranch_vccz .Lgb_slow9
	global_load_dword v7, v202, s[10:11] offset:1024 sc1
	s_mov_b32 s3, 0
	s_waitcnt vmcnt(1)
	v_and_b32_e32 v3, 31, v6
	v_and_b32_e32 v6, 0xffffffe0, v6
	v_cmp_eq_u32_e32 vcc, 31, v3
	v_add_u32_e32 v6, 32, v6
	s_cbranch_vccz .Lgb_poll9
	global_atomic_add v203, v205, s[10:11] offset:1024
	s_branch .Lgb_done9
.Lgb_poll9:
	s_waitcnt vmcnt(0)
	v_sub_u32_e32 v3, v7, v6
	v_cmp_gt_i32_e32 vcc, 0, v3
	s_cbranch_vccz .Lgb_done9
	s_sleep 1
	s_add_u32 s3, s3, 1
	s_cmp_lt_u32 s3, 0x40000
	s_cbranch_scc0 .Lgb_done9
	global_load_dword v7, v202, s[10:11] offset:1024 sc1
	s_branch .Lgb_poll9

; #define LAS __attribute__((address_space(3)))
; __global__ void __launch_bounds__(NTHREADS, 2) hybrid_fwd(Args Aval) {
;     ...
;         {   PHASE_BEGIN
;             const pg8::bf16_t* W = (const pg8::bf16_t*)(ws + WS_W1) + (size_t)l * DFF * DM;
;             pg8::Gemm g{(const pg8::bf16_t*)(ws + WS_XB), W, MP, DFF, DM}; pg8::GroupOrder S{8, 16, grp, rank, true};
;             pg8::BigEpi<pg8::RsBf16R8<1>> E{{(pg8::bf16_t*)(ws + WS_H1), DFF, (const float*)(ws + WS_SSQ), (const LAS float*)(lds + 131072)}};
;             RS_TABLE();
.LBB0_1369:
	s_or_b64 exec, exec, s[0:1]
	s_mov_b64 s[0:1], s[48:49]
	s_mov_b32 s3, s2
	v_mov_b32_e32 v152, v0
	s_waitcnt vmcnt(0)
	s_barrier
	s_load_dwordx2 s[4:5], s[0:1], 0x110
	s_and_b32 s27, s3, 7
	s_ashr_i32 s40, s3, 3
	s_movk_i32 s0, 0x100
	v_readfirstlane_b32 s41, v152
	s_waitcnt lgkmcnt(0)
	s_add_u32 s8, s4, 0x2e200000
	s_addc_u32 s9, s5, 0
	v_cmp_gt_i32_e32 vcc, s0, v152
	s_and_saveexec_b64 s[0:1], vcc
	s_cbranch_execz .LBB0_1371
	s_lshl_b32 s11, s40, 8
	s_lshl_b32 s10, s27, 11
	s_and_b32 s11, s11, 0x700
	s_or_b32 s10, s11, s10
	v_add_u32_e32 v4, s10, v152
	v_ashrrev_i32_e32 v5, 31, v4
	v_lshlrev_b64 v[4:5], 7, v[4:5]
	v_lshl_add_u64 v[20:21], s[8:9], 0, v[4:5]
	global_load_dwordx4 v[4:7], v[20:21], off offset:48
	global_load_dwordx4 v[8:11], v[20:21], off offset:32
	global_load_dwordx4 v[12:15], v[20:21], off
	global_load_dwordx4 v[16:19], v[20:21], off offset:16
	s_waitcnt vmcnt(3)
	v_add_f32_e32 v26, v4, v5
	v_add_f32_e32 v28, v6, v7
	s_waitcnt vmcnt(1)
	v_mov_b32_e32 v22, v12
	s_waitcnt vmcnt(0)
	v_mov_b32_e32 v23, v16
	v_mov_b32_e32 v16, v13
	v_pk_add_f32 v[12:13], v[22:23], v[16:17]
	v_mov_b32_e32 v16, v14
	v_mov_b32_e32 v17, v18
	v_mov_b32_e32 v18, v15
	v_pk_add_f32 v[14:15], v[16:17], v[18:19]
	s_nop 0
	v_pk_add_f32 v[12:13], v[12:13], v[14:15]
	s_nop 0
	v_add_f32_e32 v3, 0, v12
	v_add_f32_e32 v22, v3, v13
	v_mov_b32_e32 v12, v9
	v_mov_b32_e32 v13, v10
	v_mov_b32_e32 v9, v11
	v_pk_add_f32 v[8:9], v[12:13], v[8:9]
	s_nop 0
	v_pk_add_f32 v[24:25], v[8:9], v[8:9] op_sel:[0,1] op_sel_hi:[1,0]
	global_load_dwordx4 v[4:7], v[20:21], off offset:112
	global_load_dwordx4 v[8:11], v[20:21], off offset:96
	global_load_dwordx4 v[12:15], v[20:21], off offset:80
	global_load_dwordx4 v[16:19], v[20:21], off offset:64
	s_waitcnt vmcnt(2)
	v_add_f32_e32 v8, v8, v9
	v_add_f32_e32 v10, v10, v11
	s_waitcnt vmcnt(0)
	v_mov_b32_e32 v23, v16
	v_mov_b32_e32 v25, v17
	v_mov_b32_e32 v27, v18
	v_mov_b32_e32 v29, v19
	v_pk_add_f32 v[16:17], v[22:23], v[24:25]
	v_pk_add_f32 v[18:19], v[26:27], v[28:29]
	v_mov_b32_e32 v9, v6
	v_pk_add_f32 v[16:17], v[16:17], v[18:19]
	v_mov_b32_e32 v18, v13
	v_mov_b32_e32 v19, v14
	v_mov_b32_e32 v13, v15
	v_pk_add_f32 v[12:13], v[18:19], v[12:13]
	v_pk_add_f32 v[16:17], v[16:17], v[16:17] op_sel:[0,1] op_sel_hi:[1,0]
	v_pk_add_f32 v[12:13], v[12:13], v[12:13] op_sel:[0,1] op_sel_hi:[1,0]
	v_mov_b32_e32 v17, v4
	v_mov_b32_e32 v13, v5
	v_mov_b32_e32 v11, v7
	v_pk_add_f32 v[4:5], v[16:17], v[12:13]
	v_pk_add_f32 v[6:7], v[8:9], v[10:11]
	s_nop 0
	v_pk_add_f32 v[4:5], v[4:5], v[6:7]
	s_nop 0
	v_add_f32_e32 v3, v4, v5
	v_fmamk_f32 v3, v3, 0x3a800000, v1
	v_rsq_f32_e32 v3, v3
	v_lshl_add_u32 v4, v152, 2, 0
	v_add_u32_e32 v4, 0x20000, v4
	ds_write_b32 v4, v3

; #define LAS __attribute__((address_space(3)))
; template <int RA, int NP, int NS, int KT, class R8>
; DI void small_gemm(LAS unsigned char* lds, const bf16* __restrict__ A, const bf16* __restrict__ Bt, int K, int row_base, int col_base, const R8& e, int tid, int wave, int lane) {
;     ...
;     for (int st = 0; st < NT; ++st) {
;         asm volatile("s_waitcnt vmcnt(%0)" :: "n"((NS - 2) * L) : "memory");
;         __builtin_amdgcn_s_barrier();
;         asm volatile("" ::: "memory");
;         { const int nslot = (st + NS - 1) % NS; SG_STAGE(st + NS - 1, nslot); }
;         const LAS unsigned char* sb0 = lds + (st % NS) * STAGE;
; #pragma unroll
;         for (int t = 0; t < KT; ++t) {
;             const LAS unsigned char* sb = sb0 + t * SUB;
;             bf16x8 af[RA][2], bfr[NP][2][2];
; #pragma unroll
;             for (int ra = 0; ra < RA; ++ra) { af[ra][0] = *(const LAS bf16x8*)(sb + aoff[ra]); af[ra][1] = *(const LAS bf16x8*)(sb + aoff[ra] + 1024); }
; #pragma unroll
;             for (int np = 0; np < NP; ++np)
; #pragma unroll
;                 for (int n = 0; n < 2; ++n) { bfr[np][n][0] = *(const LAS bf16x8*)(sb + boff[np][n]); bfr[np][n][1] = *(const LAS bf16x8*)(sb + boff[np][n] + 1024); }
; #pragma unroll
;             for (int ks = 0; ks < 2; ++ks)
; #pragma unroll
;                 for (int ra = 0; ra < RA; ++ra)
; #pragma unroll
;                     for (int np = 0; np < NP; ++np) { acc[ra][np][0] = __builtin_amdgcn_mfma_f32_16x16x32_bf16(bfr[np][0][ks], af[ra][ks], acc[ra][np][0], 0, 0, 0); acc[ra][np][1] = __builtin_amdgcn_mfma_f32_16x16x32_bf16(bfr[np][1][ks], af[ra][ks], acc[ra][np][1], 0, 0, 0); }
;         }
;     }
.LBB0_1388:
	s_mul_i32 s15, s7, 0xab
	s_bfe_u32 s15, s15, 0x70009
	s_mul_i32 s15, s15, 3
	s_sub_i32 s15, s7, s15
	s_and_b32 s15, s15, 0xff
	s_and_b32 s16, s10, 0x3c0
	s_mul_i32 s15, s15, 0xa000
	s_lshl_b32 s34, s16, 1
	s_add_i32 s15, s6, s15
	s_waitcnt vmcnt(5)
	s_barrier
	v_lshl_add_u64 v[52:53], v[42:43], 0, s[34:35]
	s_mov_b32 m0, s15
	v_lshl_add_u64 v[54:55], v[40:41], 0, s[34:35]
	global_load_lds_dwordx4 v[52:53], off
	s_add_i32 m0, s15, 0x2000
	v_lshl_add_u64 v[56:57], v[54:55], 0, s[58:59]
	global_load_lds_dwordx4 v[54:55], off
	s_add_i32 m0, s15, 0x4000
	v_lshl_add_u64 v[58:59], v[54:55], 0, s[50:51]
	global_load_lds_dwordx4 v[56:57], off
	s_add_i32 m0, s15, 0x6000
	v_lshl_add_u64 v[60:61], v[54:55], 0, s[60:61]
	global_load_lds_dwordx4 v[58:59], off
	s_add_i32 m0, s15, 0x8000
	s_mul_hi_u32 s14, s11, 0xaaaaaaab
	global_load_lds_dwordx4 v[60:61], off
	s_lshr_b32 s14, s14, 1
	s_mul_i32 s14, s14, 0x1e000
	s_add_i32 s18, s8, s9
	v_subrev_u32_e32 v62, s14, v48
	s_add_i32 s17, s9, 0
	v_subrev_u32_e32 v63, s14, v51
	v_subrev_u32_e32 v64, s14, v49
	v_add_u32_e32 v74, s18, v62
	v_add_u32_e32 v72, s17, v64
	v_add_u32_e32 v73, s17, v63
	ds_read_b128 v[52:55], v74 offset:8192
	ds_read_b128 v[56:59], v72
	ds_read_b128 v[60:63], v74 offset:10240
	ds_read_b128 v[64:67], v74 offset:12288
	ds_read_b128 v[68:71], v74 offset:14336
	s_waitcnt lgkmcnt(0)
	v_mfma_f32_16x16x32_bf16 v[28:31], v[52:55], v[56:59], v[28:31]
	s_add_i32 s11, s11, 1
	s_add_i32 s9, s9, 0xa000
	s_add_i32 s10, s10, 64
	v_mfma_f32_16x16x32_bf16 v[32:35], v[60:63], v[56:59], v[32:35]
	s_add_i32 s7, s7, 1
	s_cmp_lg_u32 s9, 0xa0000
	v_mfma_f32_16x16x32_bf16 v[20:23], v[64:67], v[56:59], v[20:23]
	v_mfma_f32_16x16x32_bf16 v[24:27], v[68:71], v[56:59], v[24:27]
	ds_read_b128 v[56:59], v73
	s_waitcnt lgkmcnt(0)
	v_mfma_f32_16x16x32_bf16 v[12:15], v[52:55], v[56:59], v[12:15]
	v_subrev_u32_e32 v52, s14, v50
	v_add_u32_e32 v73, s17, v52
	ds_read_b128 v[52:55], v74 offset:9216
	v_mfma_f32_16x16x32_bf16 v[16:19], v[60:63], v[56:59], v[16:19]
	ds_read_b128 v[60:63], v74 offset:11264
	v_mfma_f32_16x16x32_bf16 v[4:7], v[64:67], v[56:59], v[4:7]
	ds_read_b128 v[64:67], v74 offset:13312
	v_mfma_f32_16x16x32_bf16 v[8:11], v[68:71], v[56:59], v[8:11]
	ds_read_b128 v[68:71], v74 offset:15360
	ds_read_b128 v[56:59], v72 offset:1024
	s_waitcnt lgkmcnt(0)
	v_mfma_f32_16x16x32_bf16 v[28:31], v[52:55], v[56:59], v[28:31]
	v_mfma_f32_16x16x32_bf16 v[32:35], v[60:63], v[56:59], v[32:35]
	v_mfma_f32_16x16x32_bf16 v[20:23], v[64:67], v[56:59], v[20:23]
	v_mfma_f32_16x16x32_bf16 v[24:27], v[68:71], v[56:59], v[24:27]
	ds_read_b128 v[56:59], v73
	s_waitcnt lgkmcnt(0)
	v_mfma_f32_16x16x32_bf16 v[12:15], v[52:55], v[56:59], v[12:15]
	v_mfma_f32_16x16x32_bf16 v[16:19], v[60:63], v[56:59], v[16:19]
	v_mfma_f32_16x16x32_bf16 v[4:7], v[64:67], v[56:59], v[4:7]
	v_mfma_f32_16x16x32_bf16 v[8:11], v[68:71], v[56:59], v[8:11]
	s_cbranch_scc1 .LBB0_1388
; DI u32x4 pack8(const f32x4 v0, const f32x4 v1) { u32x4 w; w.x = pk2(v0[0], v0[1]); w.y = pk2(v0[2], v0[3]); w.z = pk2(v1[0], v1[1]); w.w = pk2(v1[2], v1[3]); return w; }
;     DI void row8(int row, int col, f32x4 v0, f32x4 v1, float, int fq) const { row8p(row, col, v0, v1, pre(row, col), fq); }
;     DI void row8(int row, int col, f32x4 v0, f32x4 v1, float r, int) const {
;         v0 = v0 * r; v1 = v1 * r;
;         if (MODE == 1) {
; #pragma unroll
;             for (int j = 0; j < 4; ++j) { const float a = v0[j] > 0.f ? v0[j] : 0.f, b = v1[j] > 0.f ? v1[j] : 0.f; v0[j] = a * a; v1[j] = b * b; } }
;         *(u32x4*)(O + (size_t)row * ldc + col) = pack8(v0, v1);
; __device__ __forceinline__ void grp_barrier(const XcdBarrier& b, unsigned gsz) {
;     asm volatile("s_waitcnt vmcnt(0)" ::: "memory");
;     __syncthreads();
;     if (threadIdx.x == 0) {
;         unsigned* bar = b.bar;
;         __builtin_amdgcn_s_waitcnt(0);
;         unsigned nloc = b.st[0], nx = b.st[1];
;         if (nloc == 0u) { grp_barrier_complete(bar, b.x, gsz, nloc, nx); b.st[0] = nloc; b.st[1] = nx; }
	v_add_f32_e32 v41, v44, v45
	v_add_f32_e32 v40, v46, v47
	v_mov_b32_e32 v42, v41
	v_mov_b32_e32 v43, v40
	s_nop 0
	v_permlane32_swap_b32_e32 v41, v42
	v_permlane32_swap_b32_e32 v40, v43
	v_add_f32_e32 v40, v40, v43
	v_add_f32_e32 v41, v41, v42
	v_fmamk_f32 v40, v40, 0x3a800000, v1
	v_fmamk_f32 v41, v41, 0x3a800000, v1
	v_rsq_f32_e32 v40, v40
	v_rsq_f32_e32 v42, v41
	s_lshl_b32 s6, s13, 2
	s_sub_i32 s6, s12, s6
	s_lshl_b32 s6, s6, 6
	v_pk_mul_f32 v[30:31], v[42:43], v[30:31] op_sel_hi:[0,1]
	v_pk_mul_f32 v[28:29], v[42:43], v[28:29] op_sel_hi:[0,1]
	v_pk_mul_f32 v[32:33], v[42:43], v[32:33] op_sel_hi:[0,1]
	v_pk_mul_f32 v[14:15], v[40:41], v[14:15] op_sel_hi:[0,1]
	v_pk_mul_f32 v[12:13], v[40:41], v[12:13] op_sel_hi:[0,1]
	v_pk_mul_f32 v[16:17], v[40:41], v[16:17] op_sel_hi:[0,1]
	s_add_i32 s6, s6, s3
	v_pk_mul_f32 v[34:35], v[42:43], v[34:35] op_sel_hi:[0,1]
	v_max_f32_e32 v29, 0, v29
	v_max_f32_e32 v28, 0, v28
	v_max_f32_e32 v33, 0, v33
	v_max_f32_e32 v32, 0, v32
	v_max_f32_e32 v31, 0, v31
	v_max_f32_e32 v30, 0, v30
	v_max_f32_e32 v13, 0, v13
	v_max_f32_e32 v12, 0, v12
	v_max_f32_e32 v17, 0, v17
	v_max_f32_e32 v16, 0, v16
	v_max_f32_e32 v15, 0, v15
	v_max_f32_e32 v14, 0, v14
	v_or_b32_e32 v44, s6, v3
	v_pk_mul_f32 v[28:29], v[28:29], v[28:29]
	v_pk_mul_f32 v[32:33], v[32:33], v[32:33]
	v_pk_mul_f32 v[30:31], v[30:31], v[30:31]
	v_max_f32_e32 v35, 0, v35
	v_max_f32_e32 v34, 0, v34
	v_pk_mul_f32 v[22:23], v[42:43], v[22:23] op_sel_hi:[0,1]
	v_pk_mul_f32 v[20:21], v[42:43], v[20:21] op_sel_hi:[0,1]
	v_pk_mul_f32 v[26:27], v[42:43], v[26:27] op_sel_hi:[0,1]
	v_pk_mul_f32 v[24:25], v[42:43], v[24:25] op_sel_hi:[0,1]
	v_pk_mul_f32 v[18:19], v[40:41], v[18:19] op_sel_hi:[0,1]
	v_pk_mul_f32 v[12:13], v[12:13], v[12:13]
	v_pk_mul_f32 v[16:17], v[16:17], v[16:17]
	v_pk_mul_f32 v[14:15], v[14:15], v[14:15]
	v_pk_mul_f32 v[6:7], v[40:41], v[6:7] op_sel_hi:[0,1]
	v_pk_mul_f32 v[4:5], v[40:41], v[4:5] op_sel_hi:[0,1]
	v_pk_mul_f32 v[10:11], v[40:41], v[10:11] op_sel_hi:[0,1]
	v_pk_mul_f32 v[8:9], v[40:41], v[8:9] op_sel_hi:[0,1]
	v_pk_mul_f32 v[34:35], v[34:35], v[34:35]
	v_cvt_pk_bf16_f32 v28, v28, v29
	v_cvt_pk_bf16_f32 v29, v30, v31
	v_cvt_pk_bf16_f32 v30, v32, v33
	v_lshlrev_b64 v[32:33], 13, v[38:39]
	v_ashrrev_i32_e32 v45, 31, v44
	v_max_f32_e32 v21, 0, v21
	v_max_f32_e32 v20, 0, v20
	v_max_f32_e32 v25, 0, v25
	v_max_f32_e32 v24, 0, v24
	v_max_f32_e32 v23, 0, v23
	v_max_f32_e32 v22, 0, v22
	v_max_f32_e32 v27, 0, v27
	v_max_f32_e32 v26, 0, v26
	v_max_f32_e32 v19, 0, v19
	v_max_f32_e32 v18, 0, v18
	v_cvt_pk_bf16_f32 v12, v12, v13
	v_cvt_pk_bf16_f32 v13, v14, v15
	v_cvt_pk_bf16_f32 v14, v16, v17
	v_lshlrev_b64 v[16:17], 13, v[36:37]
	v_max_f32_e32 v5, 0, v5
	v_max_f32_e32 v4, 0, v4
	v_max_f32_e32 v9, 0, v9
	v_max_f32_e32 v8, 0, v8
	v_max_f32_e32 v7, 0, v7
	v_max_f32_e32 v6, 0, v6
	v_max_f32_e32 v11, 0, v11
	v_max_f32_e32 v10, 0, v10
	v_cvt_pk_bf16_f32 v31, v34, v35
	v_lshl_add_u64 v[32:33], s[4:5], 0, v[32:33]
	v_lshlrev_b64 v[34:35], 1, v[44:45]
	v_pk_mul_f32 v[20:21], v[20:21], v[20:21]
	v_pk_mul_f32 v[24:25], v[24:25], v[24:25]
	v_pk_mul_f32 v[22:23], v[22:23], v[22:23]
	v_pk_mul_f32 v[26:27], v[26:27], v[26:27]
	v_pk_mul_f32 v[18:19], v[18:19], v[18:19]
	v_lshl_add_u64 v[16:17], s[4:5], 0, v[16:17]
	v_pk_mul_f32 v[4:5], v[4:5], v[4:5]
	v_pk_mul_f32 v[8:9], v[8:9], v[8:9]
	v_pk_mul_f32 v[6:7], v[6:7], v[6:7]
	v_pk_mul_f32 v[10:11], v[10:11], v[10:11]
	v_lshl_add_u64 v[32:33], v[32:33], 0, v[34:35]
	v_cvt_pk_bf16_f32 v20, v20, v21
	v_cvt_pk_bf16_f32 v21, v22, v23
	v_cvt_pk_bf16_f32 v22, v24, v25
	v_cvt_pk_bf16_f32 v23, v26, v27
	v_cvt_pk_bf16_f32 v15, v18, v19
	v_lshl_add_u64 v[16:17], v[16:17], 0, v[34:35]
	v_cvt_pk_bf16_f32 v4, v4, v5
	v_cvt_pk_bf16_f32 v5, v6, v7
	v_cvt_pk_bf16_f32 v6, v8, v9
	v_cvt_pk_bf16_f32 v7, v10, v11
	s_mov_b64 s[4:5], s[48:49]
	s_mov_b32 s8, s2
	s_waitcnt vmcnt(0)
	s_barrier
	global_store_dwordx4 v[32:33], v[28:31], off
	global_store_dwordx4 v[32:33], v[20:23], off offset:64
	global_store_dwordx4 v[16:17], v[12:15], off
	global_store_dwordx4 v[16:17], v[4:7], off offset:64
	s_getreg_b32 s3, hwreg(HW_REG_XCC_ID, 0, 4)
	s_waitcnt vmcnt(0)
	s_waitcnt vmcnt(0)
	v_readfirstlane_b32 s6, v0
	s_nop 3
	s_lshr_b32 s6, s6, 6
	s_cmp_eq_u32 s6, 1
	s_cbranch_scc0 .Lgb_noinv10
	buffer_inv sc1

; __device__ __forceinline__ unsigned xb_ld(unsigned* p)              { return __hip_atomic_load(p, __ATOMIC_RELAXED, __HIP_MEMORY_SCOPE_AGENT); }
; #define XB_SPIN(cond, bar) do { unsigned _sp = 0; while (cond) { __builtin_amdgcn_s_sleep(1); \
;     if ((++_sp & 255u) == 0u) { if (xb_ld(&(bar)[XB_TMO])) break; if (_sp > XB_SPIN_CAP) { atomicAdd(&(bar)[XB_TMO], 1u); break; } } } } while (0)
; __device__ __forceinline__ void grp_barrier(const XcdBarrier& b, unsigned gsz) {
;     ...
;             asm volatile("s_waitcnt vmcnt(0)" ::: "memory");
;         } else {
;             XB_SPIN(xb_ld(&bar[XB_XGEN(b.x)]) == gen, bar);
;             if (!early) __builtin_amdgcn_fence(__ATOMIC_ACQUIRE, "agent");
;             asm volatile("s_waitcnt vmcnt(0)" ::: "memory");
;         }
;     }
;     __syncthreads();
.LBB0_1449:
	s_or_b64 exec, exec, s[6:7]
	s_mov_b64 s[4:5], s[48:49]
	s_mov_b32 s3, s2
	v_mov_b32_e32 v3, v0
	s_waitcnt vmcnt(0)
	s_barrier
	s_load_dwordx2 s[12:13], s[4:5], 0x110
	s_and_b32 s27, s3, 7
	s_ashr_i32 s34, s3, 3
	s_cmp_lt_i32 s34, 32
	s_cselect_b64 s[4:5], -1, 0
	s_cmp_gt_i32 s34, 31
	v_readfirstlane_b32 s14, v3
	s_cbranch_scc1 .LBB0_1451
	s_ashr_i32 s7, s34, 31
	s_lshr_b32 s7, s7, 29
	s_add_i32 s7, s34, s7
	s_ashr_i32 s24, s7, 3
	s_and_b32 s7, s7, -8
	s_lshl_b32 s6, s27, 3
	s_sub_i32 s7, s34, s7
	s_add_i32 s28, s6, s7
